# GEMM consumer rewritten for v_mfma_f32_16x16x32_bf16 (4x8 blocks of 16x16, 2 K-halves per step, permlane16 epilogue)
# speedup vs baseline: 1.1295x; 1.0228x over previous
; template <int EPI>
; __device__ __forceinline__ void gemm_phase(const Params& p, const u16* __restrict__ A, int lda, const u16* __restrict__ BT, int ldb,
;                            int K, int N, u16* __restrict__ outb, int ldo, int resid_in, int boff) {
;     ...
;     LOADX(0);
;     if (KT > 1) LOADY(1);
;     f32x16 acc00, acc01, acc10, acc11;
;     if (EPI == EPI_RES && !part_unit) {
;       const int cc0 = n0 + wn * 64 + (lane & 31);
;       float* xfq = p.out;
; #pragma unroll
;       for (int i = 0; i < 16; i++) {
;         const int row = m0 + wm * 64 + 4 * (lane >> 5) + (i & 3) + 8 * (i >> 2);
;         const float* ra = resid_in ? xrow(p, row) : (xfq + (size_t)row * 1024);
;         const float* rb = resid_in ? xrow(p, row + 32) : (xfq + (size_t)(row + 32) * 1024);
;         acc00[i] = ra[cc0]; acc01[i] = ra[cc0 + 32];
;         acc10[i] = rb[cc0]; acc11[i] = rb[cc0 + 32];
;       }
;     } else {
; #pragma unroll
;       for (int i = 0; i < 16; i++) { acc00[i] = 0.f; acc01[i] = 0.f; acc10[i] = 0.f; acc11[i] = 0.f; }
;     }
.Lgm_common:
	s_add_u32 s14, s96, 0x2e00100
	s_addc_u32 s15, s97, 0
	v_mov_b32_e32 v190, 0x1c040
	ds_read_b64 v[192:193], v190
	v_lshrrev_b32_e32 v191, 6, v128
	s_waitcnt lgkmcnt(0)
	v_readfirstlane_b32 s98, v192
	v_readfirstlane_b32 s99, v193
	v_readfirstlane_b32 s4, v191
	v_readlane_b32 s5, v254, 0
	s_nop 3
	s_cmp_ge_u32 s4, 4
	s_cbranch_scc1 .Lgm_producer
	v_and_b32_e32 v240, 63, v128
	v_lshrrev_b32_e32 v249, 4, v240
	v_and_b32_e32 v248, 15, v240
	v_bfe_u32 v238, v240, 1, 3
	v_lshlrev_b32_e32 v239, 7, v248
	s_lshl_b32 s8, s4, 13
	v_or_b32_e32 v241, 0, v249
	v_xor_b32_e32 v241, v241, v238
	v_lshlrev_b32_e32 v241, 4, v241
	v_add_u32_e32 v241, v241, v239
	v_add_u32_e32 v226, s8, v241
	v_add_u32_e32 v228, 0x8000, v241
	v_or_b32_e32 v241, 4, v249
	v_xor_b32_e32 v241, v241, v238
	v_lshlrev_b32_e32 v241, 4, v241
	v_add_u32_e32 v241, v241, v239
	v_add_u32_e32 v227, s8, v241
	v_add_u32_e32 v229, 0x8000, v241
	v_lshlrev_b32_e32 v242, 2, v248
	s_lshl_b32 s10, s4, 8
	s_add_u32 s10, s10, 0x24000
	v_add_u32_e32 v242, s10, v242
	s_mov_b32 s13, 0
	s_mov_b32 s31, 0xc000
	s_mov_b32 s35, 0xc000
	s_mov_b32 s34, 0xfffe8000
	s_mov_b32 s33, 0
	v_mov_b64_e32 v[0:1], 0
	v_mov_b64_e32 v[2:3], 0
	v_mov_b64_e32 v[4:5], 0
	v_mov_b64_e32 v[6:7], 0
	v_mov_b64_e32 v[8:9], 0
	v_mov_b64_e32 v[10:11], 0
	v_mov_b64_e32 v[12:13], 0
	v_mov_b64_e32 v[14:15], 0
	v_mov_b64_e32 v[16:17], 0
	v_mov_b64_e32 v[18:19], 0
	v_mov_b64_e32 v[20:21], 0
	v_mov_b64_e32 v[22:23], 0
	v_mov_b64_e32 v[24:25], 0
	v_mov_b64_e32 v[26:27], 0
	v_mov_b64_e32 v[28:29], 0
	v_mov_b64_e32 v[30:31], 0
	v_mov_b64_e32 v[32:33], 0
	v_mov_b64_e32 v[34:35], 0
	v_mov_b64_e32 v[36:37], 0
	v_mov_b64_e32 v[38:39], 0
	v_mov_b64_e32 v[40:41], 0
	v_mov_b64_e32 v[42:43], 0
	v_mov_b64_e32 v[44:45], 0
	v_mov_b64_e32 v[46:47], 0
	v_mov_b64_e32 v[48:49], 0
	v_mov_b64_e32 v[50:51], 0
	v_mov_b64_e32 v[52:53], 0
	v_mov_b64_e32 v[54:55], 0
	v_mov_b64_e32 v[56:57], 0
	v_mov_b64_e32 v[58:59], 0
	v_mov_b64_e32 v[60:61], 0
	v_mov_b64_e32 v[62:63], 0
	v_mov_b64_e32 v[64:65], 0
	v_mov_b64_e32 v[66:67], 0
	v_mov_b64_e32 v[68:69], 0
	v_mov_b64_e32 v[70:71], 0
	v_mov_b64_e32 v[72:73], 0
	v_mov_b64_e32 v[74:75], 0
	v_mov_b64_e32 v[76:77], 0
	v_mov_b64_e32 v[78:79], 0
	v_mov_b64_e32 v[80:81], 0
	v_mov_b64_e32 v[82:83], 0
	v_mov_b64_e32 v[84:85], 0
	v_mov_b64_e32 v[86:87], 0
	v_mov_b64_e32 v[88:89], 0
	v_mov_b64_e32 v[90:91], 0
	v_mov_b64_e32 v[92:93], 0
	v_mov_b64_e32 v[94:95], 0
	v_mov_b64_e32 v[96:97], 0
	v_mov_b64_e32 v[98:99], 0
	v_mov_b64_e32 v[100:101], 0
	v_mov_b64_e32 v[102:103], 0
	v_mov_b64_e32 v[104:105], 0
	v_mov_b64_e32 v[106:107], 0
	v_mov_b64_e32 v[108:109], 0
	v_mov_b64_e32 v[110:111], 0
	v_mov_b64_e32 v[112:113], 0
	v_mov_b64_e32 v[114:115], 0
	v_mov_b64_e32 v[116:117], 0
	v_mov_b64_e32 v[118:119], 0
	v_mov_b64_e32 v[120:121], 0
	v_mov_b64_e32 v[122:123], 0
	v_mov_b64_e32 v[124:125], 0
	v_mov_b64_e32 v[126:127], 0
	v_mov_b64_e32 v[178:179], 0
	v_mov_b64_e32 v[180:181], 0
	v_mov_b64_e32 v[182:183], 0
	v_mov_b64_e32 v[184:185], 0
	v_mov_b64_e32 v[186:187], 0
	v_mov_b64_e32 v[188:189], 0
	v_mov_b64_e32 v[190:191], 0
	v_mov_b64_e32 v[192:193], 0
	v_mov_b64_e32 v[194:195], 0
	v_mov_b64_e32 v[196:197], 0
	v_mov_b64_e32 v[198:199], 0
	v_mov_b64_e32 v[200:201], 0
	v_mov_b64_e32 v[202:203], 0
	v_mov_b64_e32 v[204:205], 0
	v_mov_b64_e32 v[206:207], 0
	v_mov_b64_e32 v[208:209], 0
	v_mov_b64_e32 v[210:211], 0
	v_mov_b64_e32 v[212:213], 0
	v_mov_b64_e32 v[214:215], 0
	v_mov_b64_e32 v[216:217], 0
	v_mov_b64_e32 v[218:219], 0
	v_mov_b64_e32 v[220:221], 0
	v_mov_b64_e32 v[222:223], 0
	v_mov_b64_e32 v[224:225], 0
	s_waitcnt lgkmcnt(0)
	s_barrier

; #define RAW_BARRIER() do { asm volatile("s_waitcnt lgkmcnt(0)" ::: "memory"); __builtin_amdgcn_s_barrier(); asm volatile("" ::: "memory"); } while (0)
; template <int EPI>
; __device__ __forceinline__ void gemm_phase(const Params& p, const u16* __restrict__ A, int lda, const u16* __restrict__ BT, int ldb,
;                            int K, int N, u16* __restrict__ outb, int ldo, int resid_in, int boff) {
;     ...
;     for (int kt = 0; kt < KT; kt += 2) {
;       if (kt + 1 < KT) WRITEY(1);
;       if (kt + 3 < KT) LOADY(kt + 3);
;       COMPUTE(0);
;       RAW_BARRIER();
;       if (kt + 1 >= KT) break;
;       if (kt + 2 < KT) WRITEX(0);
;       if (kt + 4 < KT) LOADX(kt + 4);
;       COMPUTE(1);
;       RAW_BARRIER();
;     }
.Lgc_loopT:
	ds_read_b128 v[130:133], v226
	ds_read_b128 v[146:149], v228
	ds_read_b128 v[150:153], v228 offset:2048
	ds_read_b128 v[154:157], v228 offset:4096
	ds_read_b128 v[158:161], v228 offset:6144
	ds_read_b128 v[162:165], v228 offset:8192
	ds_read_b128 v[166:169], v228 offset:10240
	ds_read_b128 v[170:173], v228 offset:12288
	ds_read_b128 v[174:177], v228 offset:14336
	ds_read_b128 v[134:137], v226 offset:2048
	ds_read_b128 v[138:141], v226 offset:4096
	ds_read_b128 v[142:145], v226 offset:6144
	v_mfma_f32_16x16x32_bf16 v[0:3], v[194:197], v[178:181], v[0:3]
	v_mfma_f32_16x16x32_bf16 v[4:7], v[198:201], v[178:181], v[4:7]
	v_mfma_f32_16x16x32_bf16 v[8:11], v[202:205], v[178:181], v[8:11]
	v_mfma_f32_16x16x32_bf16 v[12:15], v[206:209], v[178:181], v[12:15]
	v_mfma_f32_16x16x32_bf16 v[16:19], v[210:213], v[178:181], v[16:19]
	v_mfma_f32_16x16x32_bf16 v[20:23], v[214:217], v[178:181], v[20:23]
	v_mfma_f32_16x16x32_bf16 v[24:27], v[218:221], v[178:181], v[24:27]
	v_mfma_f32_16x16x32_bf16 v[28:31], v[222:225], v[178:181], v[28:31]
	v_mfma_f32_16x16x32_bf16 v[32:35], v[194:197], v[182:185], v[32:35]
	v_mfma_f32_16x16x32_bf16 v[36:39], v[198:201], v[182:185], v[36:39]
	v_mfma_f32_16x16x32_bf16 v[40:43], v[202:205], v[182:185], v[40:43]
	v_mfma_f32_16x16x32_bf16 v[44:47], v[206:209], v[182:185], v[44:47]
	v_mfma_f32_16x16x32_bf16 v[48:51], v[210:213], v[182:185], v[48:51]
	v_mfma_f32_16x16x32_bf16 v[52:55], v[214:217], v[182:185], v[52:55]
	v_mfma_f32_16x16x32_bf16 v[56:59], v[218:221], v[182:185], v[56:59]
	v_mfma_f32_16x16x32_bf16 v[60:63], v[222:225], v[182:185], v[60:63]
	v_mfma_f32_16x16x32_bf16 v[64:67], v[194:197], v[186:189], v[64:67]
	v_mfma_f32_16x16x32_bf16 v[68:71], v[198:201], v[186:189], v[68:71]
	v_mfma_f32_16x16x32_bf16 v[72:75], v[202:205], v[186:189], v[72:75]
	v_mfma_f32_16x16x32_bf16 v[76:79], v[206:209], v[186:189], v[76:79]
	v_mfma_f32_16x16x32_bf16 v[80:83], v[210:213], v[186:189], v[80:83]
	v_mfma_f32_16x16x32_bf16 v[84:87], v[214:217], v[186:189], v[84:87]
	v_mfma_f32_16x16x32_bf16 v[88:91], v[218:221], v[186:189], v[88:91]
	v_mfma_f32_16x16x32_bf16 v[92:95], v[222:225], v[186:189], v[92:95]
	v_mfma_f32_16x16x32_bf16 v[96:99], v[194:197], v[190:193], v[96:99]
	v_mfma_f32_16x16x32_bf16 v[100:103], v[198:201], v[190:193], v[100:103]
	v_mfma_f32_16x16x32_bf16 v[104:107], v[202:205], v[190:193], v[104:107]
	v_mfma_f32_16x16x32_bf16 v[108:111], v[206:209], v[190:193], v[108:111]
	v_mfma_f32_16x16x32_bf16 v[112:115], v[210:213], v[190:193], v[112:115]
	v_mfma_f32_16x16x32_bf16 v[116:119], v[214:217], v[190:193], v[116:119]
	v_mfma_f32_16x16x32_bf16 v[120:123], v[218:221], v[190:193], v[120:123]
	v_mfma_f32_16x16x32_bf16 v[124:127], v[222:225], v[190:193], v[124:127]
	ds_read_b128 v[178:181], v227
	ds_read_b128 v[194:197], v229
	ds_read_b128 v[198:201], v229 offset:2048
	ds_read_b128 v[202:205], v229 offset:4096
	ds_read_b128 v[206:209], v229 offset:6144
	ds_read_b128 v[210:213], v229 offset:8192
	ds_read_b128 v[214:217], v229 offset:10240
	ds_read_b128 v[218:221], v229 offset:12288
	ds_read_b128 v[222:225], v229 offset:14336
	ds_read_b128 v[182:185], v227 offset:2048
	ds_read_b128 v[186:189], v227 offset:4096
	ds_read_b128 v[190:193], v227 offset:6144
	s_waitcnt lgkmcnt(12)
	v_mfma_f32_16x16x32_bf16 v[0:3], v[146:149], v[130:133], v[0:3]
	v_mfma_f32_16x16x32_bf16 v[4:7], v[150:153], v[130:133], v[4:7]
	v_mfma_f32_16x16x32_bf16 v[8:11], v[154:157], v[130:133], v[8:11]
	v_mfma_f32_16x16x32_bf16 v[12:15], v[158:161], v[130:133], v[12:15]
	v_mfma_f32_16x16x32_bf16 v[16:19], v[162:165], v[130:133], v[16:19]
	v_mfma_f32_16x16x32_bf16 v[20:23], v[166:169], v[130:133], v[20:23]
	v_mfma_f32_16x16x32_bf16 v[24:27], v[170:173], v[130:133], v[24:27]
	v_mfma_f32_16x16x32_bf16 v[28:31], v[174:177], v[130:133], v[28:31]
	v_mfma_f32_16x16x32_bf16 v[32:35], v[146:149], v[134:137], v[32:35]
	v_add_u32_e32 v226, s31, v226
	v_mfma_f32_16x16x32_bf16 v[36:39], v[150:153], v[134:137], v[36:39]
	v_add_u32_e32 v227, s31, v227
	v_mfma_f32_16x16x32_bf16 v[40:43], v[154:157], v[134:137], v[40:43]
	v_add_u32_e32 v228, s31, v228
	v_mfma_f32_16x16x32_bf16 v[44:47], v[158:161], v[134:137], v[44:47]
	v_add_u32_e32 v229, s31, v229
	v_mfma_f32_16x16x32_bf16 v[48:51], v[162:165], v[134:137], v[48:51]
	v_mfma_f32_16x16x32_bf16 v[52:55], v[166:169], v[134:137], v[52:55]
	v_mfma_f32_16x16x32_bf16 v[56:59], v[170:173], v[134:137], v[56:59]
	v_mfma_f32_16x16x32_bf16 v[60:63], v[174:177], v[134:137], v[60:63]
	v_mfma_f32_16x16x32_bf16 v[64:67], v[146:149], v[138:141], v[64:67]
	v_mfma_f32_16x16x32_bf16 v[68:71], v[150:153], v[138:141], v[68:71]
	v_mfma_f32_16x16x32_bf16 v[72:75], v[154:157], v[138:141], v[72:75]
	v_mfma_f32_16x16x32_bf16 v[76:79], v[158:161], v[138:141], v[76:79]
	v_mfma_f32_16x16x32_bf16 v[80:83], v[162:165], v[138:141], v[80:83]
	v_mfma_f32_16x16x32_bf16 v[84:87], v[166:169], v[138:141], v[84:87]
	v_mfma_f32_16x16x32_bf16 v[88:91], v[170:173], v[138:141], v[88:91]
	v_mfma_f32_16x16x32_bf16 v[92:95], v[174:177], v[138:141], v[92:95]
	v_mfma_f32_16x16x32_bf16 v[96:99], v[146:149], v[142:145], v[96:99]
	v_mfma_f32_16x16x32_bf16 v[100:103], v[150:153], v[142:145], v[100:103]
	v_mfma_f32_16x16x32_bf16 v[104:107], v[154:157], v[142:145], v[104:107]
	v_mfma_f32_16x16x32_bf16 v[108:111], v[158:161], v[142:145], v[108:111]
	v_mfma_f32_16x16x32_bf16 v[112:115], v[162:165], v[142:145], v[112:115]
	v_mfma_f32_16x16x32_bf16 v[116:119], v[166:169], v[142:145], v[116:119]
	v_mfma_f32_16x16x32_bf16 v[120:123], v[170:173], v[142:145], v[120:123]
	v_mfma_f32_16x16x32_bf16 v[124:127], v[174:177], v[142:145], v[124:127]
	s_add_u32 s13, s13, 1
	s_cmp_eq_u32 s13, 3
	s_cselect_b32 s13, 0, s13
	s_cmp_eq_u32 s13, 2
	s_cselect_b32 s31, s34, s35
	s_waitcnt lgkmcnt(0)
	s_barrier
; template <int EPI> ...
;     ...
;     if (EPI == EPI_SCALE || EPI == EPI_PLAIN || EPI == EPI_FF1) {
; #pragma unroll
;       for (int i = 0; i < 16; i++) {
;         const int rl = rbase + (i & 3) + 8 * (i >> 2);
;         const int row = m0 + rl;
;         float v0 = acc0[i], v1 = acc1[i];
;         if (EPI != EPI_PLAIN) { float rs = sRs[rl]; v0 *= rs; v1 *= rs; }
;         if (EPI == EPI_FF1) { v0 = fmaxf(v0, 0.f); v1 = fmaxf(v1, 0.f); v0 *= v0; v1 *= v1; }
;         outb[(size_t)row * ldo + c0] = f2bf(v0);
; template <int EPI>
; __device__ __forceinline__ void gemm_phase(const Params& p, const u16* __restrict__ A, int lda, const u16* __restrict__ BT, int ldb,
;                            int K, int N, u16* __restrict__ outb, int ldo, int resid_in, int boff) {
;     ...
;     if (EPI == EPI_SCALE || EPI == EPI_FF1) {
;       if (tid < 256) {
;         const float sq = (pq0.x + pq0.y + pq0.z + pq0.w) + (pq1.x + pq1.y + pq1.z + pq1.w) + (pq2.x + pq2.y + pq2.z + pq2.w) + (pq3.x + pq3.y + pq3.z + pq3.w);
;         sRs[tid] = rsqrtf(sq * (1.0f / 1024.0f) + 1e-6f);
;       }
;       __syncthreads();
;     }
;     const int c0 = n0 + wn * 64 + (lane & 31);
;     const int c1 = c0 + 32;
	s_sub_u32 s18, s18, 1
	s_cmp_lg_u32 s18, 0
	s_cbranch_scc1 .Lgc_loopT
	v_mfma_f32_16x16x32_bf16 v[0:3], v[194:197], v[178:181], v[0:3]
	v_mfma_f32_16x16x32_bf16 v[4:7], v[198:201], v[178:181], v[4:7]
	v_mfma_f32_16x16x32_bf16 v[8:11], v[202:205], v[178:181], v[8:11]
	v_mfma_f32_16x16x32_bf16 v[12:15], v[206:209], v[178:181], v[12:15]
	v_mfma_f32_16x16x32_bf16 v[16:19], v[210:213], v[178:181], v[16:19]
	v_mfma_f32_16x16x32_bf16 v[20:23], v[214:217], v[178:181], v[20:23]
	v_mfma_f32_16x16x32_bf16 v[24:27], v[218:221], v[178:181], v[24:27]
	v_mfma_f32_16x16x32_bf16 v[28:31], v[222:225], v[178:181], v[28:31]
	v_mfma_f32_16x16x32_bf16 v[32:35], v[194:197], v[182:185], v[32:35]
	v_mfma_f32_16x16x32_bf16 v[36:39], v[198:201], v[182:185], v[36:39]
	v_mfma_f32_16x16x32_bf16 v[40:43], v[202:205], v[182:185], v[40:43]
	v_mfma_f32_16x16x32_bf16 v[44:47], v[206:209], v[182:185], v[44:47]
	v_mfma_f32_16x16x32_bf16 v[48:51], v[210:213], v[182:185], v[48:51]
	v_mfma_f32_16x16x32_bf16 v[52:55], v[214:217], v[182:185], v[52:55]
	v_mfma_f32_16x16x32_bf16 v[56:59], v[218:221], v[182:185], v[56:59]
	v_mfma_f32_16x16x32_bf16 v[60:63], v[222:225], v[182:185], v[60:63]
	v_mfma_f32_16x16x32_bf16 v[64:67], v[194:197], v[186:189], v[64:67]
	v_mfma_f32_16x16x32_bf16 v[68:71], v[198:201], v[186:189], v[68:71]
	v_mfma_f32_16x16x32_bf16 v[72:75], v[202:205], v[186:189], v[72:75]
	v_mfma_f32_16x16x32_bf16 v[76:79], v[206:209], v[186:189], v[76:79]
	v_mfma_f32_16x16x32_bf16 v[80:83], v[210:213], v[186:189], v[80:83]
	v_mfma_f32_16x16x32_bf16 v[84:87], v[214:217], v[186:189], v[84:87]
	v_mfma_f32_16x16x32_bf16 v[88:91], v[218:221], v[186:189], v[88:91]
	v_mfma_f32_16x16x32_bf16 v[92:95], v[222:225], v[186:189], v[92:95]
	v_mfma_f32_16x16x32_bf16 v[96:99], v[194:197], v[190:193], v[96:99]
	v_mfma_f32_16x16x32_bf16 v[100:103], v[198:201], v[190:193], v[100:103]
	v_mfma_f32_16x16x32_bf16 v[104:107], v[202:205], v[190:193], v[104:107]
	v_mfma_f32_16x16x32_bf16 v[108:111], v[206:209], v[190:193], v[108:111]
	v_mfma_f32_16x16x32_bf16 v[112:115], v[210:213], v[190:193], v[112:115]
	v_mfma_f32_16x16x32_bf16 v[116:119], v[214:217], v[190:193], v[116:119]
	v_mfma_f32_16x16x32_bf16 v[120:123], v[218:221], v[190:193], v[120:123]
	v_mfma_f32_16x16x32_bf16 v[124:127], v[222:225], v[190:193], v[124:127]
	s_cmp_eq_u32 s30, 3
	s_cbranch_scc1 .Lgc_epi_res
	s_lshl_b32 s11, s6, 8
	s_lshl_b32 s12, s4, 6
	s_add_u32 s11, s11, s12
	v_add_u32_e32 v238, s11, v248
	v_mul_lo_u32 v230, v238, s24
	s_lshl_b32 s11, s7, 7
	v_and_b32_e32 v239, 1, v249
	v_lshrrev_b32_e32 v240, 1, v249
	v_lshlrev_b32_e32 v239, 4, v239
	v_lshl_add_u32 v239, v240, 3, v239
	v_add_u32_e32 v239, s11, v239
	v_lshlrev_b32_e32 v239, 1, v239
	v_add_u32_e32 v230, v230, v239
	s_lshl_b32 s11, s24, 4
	v_add_u32_e32 v231, s11, v230
	v_add_u32_e32 v232, s11, v231
	v_add_u32_e32 v233, s11, v232
	s_nop 7
	v_add_u32_e32 v239, s33, v242
	ds_read_b32 v234, v239
	ds_read_b32 v235, v239 offset:64
	ds_read_b32 v236, v239 offset:128
	ds_read_b32 v237, v239 offset:192
	s_waitcnt lgkmcnt(0)
	v_mul_f32_e32 v0, v0, v234
	v_mul_f32_e32 v1, v1, v234
	v_mul_f32_e32 v2, v2, v234
	v_mul_f32_e32 v3, v3, v234
	v_mul_f32_e32 v4, v4, v234
	v_mul_f32_e32 v5, v5, v234
	v_mul_f32_e32 v6, v6, v234
	v_mul_f32_e32 v7, v7, v234
	v_mul_f32_e32 v8, v8, v234
	v_mul_f32_e32 v9, v9, v234
	v_mul_f32_e32 v10, v10, v234
	v_mul_f32_e32 v11, v11, v234
	v_mul_f32_e32 v12, v12, v234
	v_mul_f32_e32 v13, v13, v234
	v_mul_f32_e32 v14, v14, v234
	v_mul_f32_e32 v15, v15, v234
	v_mul_f32_e32 v16, v16, v234
	v_mul_f32_e32 v17, v17, v234
	v_mul_f32_e32 v18, v18, v234
	v_mul_f32_e32 v19, v19, v234
	v_mul_f32_e32 v20, v20, v234
	v_mul_f32_e32 v21, v21, v234
	v_mul_f32_e32 v22, v22, v234
	v_mul_f32_e32 v23, v23, v234
	v_mul_f32_e32 v24, v24, v234
	v_mul_f32_e32 v25, v25, v234
	v_mul_f32_e32 v26, v26, v234
	v_mul_f32_e32 v27, v27, v234
	v_mul_f32_e32 v28, v28, v234
	v_mul_f32_e32 v29, v29, v234
	v_mul_f32_e32 v30, v30, v234
	v_mul_f32_e32 v31, v31, v234
	v_mul_f32_e32 v32, v32, v235
	v_mul_f32_e32 v33, v33, v235
	v_mul_f32_e32 v34, v34, v235
	v_mul_f32_e32 v35, v35, v235
	v_mul_f32_e32 v36, v36, v235
	v_mul_f32_e32 v37, v37, v235
	v_mul_f32_e32 v38, v38, v235
	v_mul_f32_e32 v39, v39, v235
	v_mul_f32_e32 v40, v40, v235
	v_mul_f32_e32 v41, v41, v235
	v_mul_f32_e32 v42, v42, v235
	v_mul_f32_e32 v43, v43, v235
	v_mul_f32_e32 v44, v44, v235
	v_mul_f32_e32 v45, v45, v235
	v_mul_f32_e32 v46, v46, v235
	v_mul_f32_e32 v47, v47, v235
	v_mul_f32_e32 v48, v48, v235
	v_mul_f32_e32 v49, v49, v235
	v_mul_f32_e32 v50, v50, v235
	v_mul_f32_e32 v51, v51, v235
	v_mul_f32_e32 v52, v52, v235
	v_mul_f32_e32 v53, v53, v235
	v_mul_f32_e32 v54, v54, v235
	v_mul_f32_e32 v55, v55, v235
	v_mul_f32_e32 v56, v56, v235
	v_mul_f32_e32 v57, v57, v235
	v_mul_f32_e32 v58, v58, v235
	v_mul_f32_e32 v59, v59, v235
	v_mul_f32_e32 v60, v60, v235
	v_mul_f32_e32 v61, v61, v235
	v_mul_f32_e32 v62, v62, v235
	v_mul_f32_e32 v63, v63, v235
	v_mul_f32_e32 v64, v64, v236
	v_mul_f32_e32 v65, v65, v236
	v_mul_f32_e32 v66, v66, v236
	v_mul_f32_e32 v67, v67, v236
	v_mul_f32_e32 v68, v68, v236
	v_mul_f32_e32 v69, v69, v236
	v_mul_f32_e32 v70, v70, v236
	v_mul_f32_e32 v71, v71, v236
	v_mul_f32_e32 v72, v72, v236
	v_mul_f32_e32 v73, v73, v236
	v_mul_f32_e32 v74, v74, v236
	v_mul_f32_e32 v75, v75, v236
	v_mul_f32_e32 v76, v76, v236
	v_mul_f32_e32 v77, v77, v236
	v_mul_f32_e32 v78, v78, v236
	v_mul_f32_e32 v79, v79, v236
	v_mul_f32_e32 v80, v80, v236
	v_mul_f32_e32 v81, v81, v236
	v_mul_f32_e32 v82, v82, v236
	v_mul_f32_e32 v83, v83, v236
	v_mul_f32_e32 v84, v84, v236
	v_mul_f32_e32 v85, v85, v236
	v_mul_f32_e32 v86, v86, v236
	v_mul_f32_e32 v87, v87, v236
	v_mul_f32_e32 v88, v88, v236
	v_mul_f32_e32 v89, v89, v236
	v_mul_f32_e32 v90, v90, v236
	v_mul_f32_e32 v91, v91, v236
	v_mul_f32_e32 v92, v92, v236
	v_mul_f32_e32 v93, v93, v236
	v_mul_f32_e32 v94, v94, v236
	v_mul_f32_e32 v95, v95, v236
	v_mul_f32_e32 v96, v96, v237
	v_mul_f32_e32 v97, v97, v237
	v_mul_f32_e32 v98, v98, v237
	v_mul_f32_e32 v99, v99, v237
	v_mul_f32_e32 v100, v100, v237
	v_mul_f32_e32 v101, v101, v237
	v_mul_f32_e32 v102, v102, v237
	v_mul_f32_e32 v103, v103, v237
	v_mul_f32_e32 v104, v104, v237
	v_mul_f32_e32 v105, v105, v237
	v_mul_f32_e32 v106, v106, v237
	v_mul_f32_e32 v107, v107, v237
	v_mul_f32_e32 v108, v108, v237
	v_mul_f32_e32 v109, v109, v237
	v_mul_f32_e32 v110, v110, v237
	v_mul_f32_e32 v111, v111, v237
	v_mul_f32_e32 v112, v112, v237
	v_mul_f32_e32 v113, v113, v237
	v_mul_f32_e32 v114, v114, v237
	v_mul_f32_e32 v115, v115, v237
	v_mul_f32_e32 v116, v116, v237
	v_mul_f32_e32 v117, v117, v237
	v_mul_f32_e32 v118, v118, v237
	v_mul_f32_e32 v119, v119, v237
	v_mul_f32_e32 v120, v120, v237
	v_mul_f32_e32 v121, v121, v237
	v_mul_f32_e32 v122, v122, v237
	v_mul_f32_e32 v123, v123, v237
	v_mul_f32_e32 v124, v124, v237
	v_mul_f32_e32 v125, v125, v237
	v_mul_f32_e32 v126, v126, v237
	v_mul_f32_e32 v127, v127, v237
	s_cmp_eq_u32 s30, 0
	s_cbranch_scc1 .Lgm_norelu
; template <int EPI> ...
;     ...
;         if (EPI == EPI_FF1) { v0 = fmaxf(v0, 0.f); v1 = fmaxf(v1, 0.f); v0 *= v0; v1 *= v1; }
	v_max_f32_e32 v0, 0, v0
	v_mul_f32_e32 v0, v0, v0
	v_max_f32_e32 v1, 0, v1
	v_mul_f32_e32 v1, v1, v1
	v_max_f32_e32 v2, 0, v2
	v_mul_f32_e32 v2, v2, v2
	v_max_f32_e32 v3, 0, v3
	v_mul_f32_e32 v3, v3, v3
	v_max_f32_e32 v4, 0, v4
	v_mul_f32_e32 v4, v4, v4
	v_max_f32_e32 v5, 0, v5
	v_mul_f32_e32 v5, v5, v5
	v_max_f32_e32 v6, 0, v6
	v_mul_f32_e32 v6, v6, v6
	v_max_f32_e32 v7, 0, v7
	v_mul_f32_e32 v7, v7, v7
	v_max_f32_e32 v8, 0, v8
	v_mul_f32_e32 v8, v8, v8
	v_max_f32_e32 v9, 0, v9
	v_mul_f32_e32 v9, v9, v9
	v_max_f32_e32 v10, 0, v10
	v_mul_f32_e32 v10, v10, v10
	v_max_f32_e32 v11, 0, v11
	v_mul_f32_e32 v11, v11, v11
	v_max_f32_e32 v12, 0, v12
	v_mul_f32_e32 v12, v12, v12
	v_max_f32_e32 v13, 0, v13
	v_mul_f32_e32 v13, v13, v13
	v_max_f32_e32 v14, 0, v14
	v_mul_f32_e32 v14, v14, v14
	v_max_f32_e32 v15, 0, v15
	v_mul_f32_e32 v15, v15, v15
	v_max_f32_e32 v16, 0, v16
	v_mul_f32_e32 v16, v16, v16
	v_max_f32_e32 v17, 0, v17
	v_mul_f32_e32 v17, v17, v17
	v_max_f32_e32 v18, 0, v18
	v_mul_f32_e32 v18, v18, v18
	v_max_f32_e32 v19, 0, v19
	v_mul_f32_e32 v19, v19, v19
	v_max_f32_e32 v20, 0, v20
	v_mul_f32_e32 v20, v20, v20
	v_max_f32_e32 v21, 0, v21
	v_mul_f32_e32 v21, v21, v21
	v_max_f32_e32 v22, 0, v22
	v_mul_f32_e32 v22, v22, v22
	v_max_f32_e32 v23, 0, v23
	v_mul_f32_e32 v23, v23, v23
	v_max_f32_e32 v24, 0, v24
	v_mul_f32_e32 v24, v24, v24
	v_max_f32_e32 v25, 0, v25
	v_mul_f32_e32 v25, v25, v25
	v_max_f32_e32 v26, 0, v26
	v_mul_f32_e32 v26, v26, v26
	v_max_f32_e32 v27, 0, v27
	v_mul_f32_e32 v27, v27, v27
	v_max_f32_e32 v28, 0, v28
	v_mul_f32_e32 v28, v28, v28
	v_max_f32_e32 v29, 0, v29
	v_mul_f32_e32 v29, v29, v29
	v_max_f32_e32 v30, 0, v30
	v_mul_f32_e32 v30, v30, v30
	v_max_f32_e32 v31, 0, v31
	v_mul_f32_e32 v31, v31, v31
	v_max_f32_e32 v32, 0, v32
	v_mul_f32_e32 v32, v32, v32
	v_max_f32_e32 v33, 0, v33
	v_mul_f32_e32 v33, v33, v33
	v_max_f32_e32 v34, 0, v34
	v_mul_f32_e32 v34, v34, v34
	v_max_f32_e32 v35, 0, v35
	v_mul_f32_e32 v35, v35, v35
	v_max_f32_e32 v36, 0, v36
	v_mul_f32_e32 v36, v36, v36
	v_max_f32_e32 v37, 0, v37
	v_mul_f32_e32 v37, v37, v37
	v_max_f32_e32 v38, 0, v38
	v_mul_f32_e32 v38, v38, v38
	v_max_f32_e32 v39, 0, v39
	v_mul_f32_e32 v39, v39, v39
	v_max_f32_e32 v40, 0, v40
	v_mul_f32_e32 v40, v40, v40
	v_max_f32_e32 v41, 0, v41
	v_mul_f32_e32 v41, v41, v41
	v_max_f32_e32 v42, 0, v42
	v_mul_f32_e32 v42, v42, v42
	v_max_f32_e32 v43, 0, v43
	v_mul_f32_e32 v43, v43, v43
	v_max_f32_e32 v44, 0, v44
	v_mul_f32_e32 v44, v44, v44
	v_max_f32_e32 v45, 0, v45
	v_mul_f32_e32 v45, v45, v45
	v_max_f32_e32 v46, 0, v46
	v_mul_f32_e32 v46, v46, v46
	v_max_f32_e32 v47, 0, v47
	v_mul_f32_e32 v47, v47, v47
	v_max_f32_e32 v48, 0, v48
	v_mul_f32_e32 v48, v48, v48
	v_max_f32_e32 v49, 0, v49
	v_mul_f32_e32 v49, v49, v49
	v_max_f32_e32 v50, 0, v50
	v_mul_f32_e32 v50, v50, v50
	v_max_f32_e32 v51, 0, v51
	v_mul_f32_e32 v51, v51, v51
	v_max_f32_e32 v52, 0, v52
	v_mul_f32_e32 v52, v52, v52
	v_max_f32_e32 v53, 0, v53
	v_mul_f32_e32 v53, v53, v53
	v_max_f32_e32 v54, 0, v54
	v_mul_f32_e32 v54, v54, v54
	v_max_f32_e32 v55, 0, v55
	v_mul_f32_e32 v55, v55, v55
	v_max_f32_e32 v56, 0, v56
	v_mul_f32_e32 v56, v56, v56
	v_max_f32_e32 v57, 0, v57
	v_mul_f32_e32 v57, v57, v57
	v_max_f32_e32 v58, 0, v58
	v_mul_f32_e32 v58, v58, v58
	v_max_f32_e32 v59, 0, v59
	v_mul_f32_e32 v59, v59, v59
	v_max_f32_e32 v60, 0, v60
	v_mul_f32_e32 v60, v60, v60
	v_max_f32_e32 v61, 0, v61
	v_mul_f32_e32 v61, v61, v61
	v_max_f32_e32 v62, 0, v62
	v_mul_f32_e32 v62, v62, v62
	v_max_f32_e32 v63, 0, v63
	v_mul_f32_e32 v63, v63, v63
	v_max_f32_e32 v64, 0, v64
	v_mul_f32_e32 v64, v64, v64
	v_max_f32_e32 v65, 0, v65
	v_mul_f32_e32 v65, v65, v65
	v_max_f32_e32 v66, 0, v66
	v_mul_f32_e32 v66, v66, v66
	v_max_f32_e32 v67, 0, v67
	v_mul_f32_e32 v67, v67, v67
	v_max_f32_e32 v68, 0, v68
	v_mul_f32_e32 v68, v68, v68
	v_max_f32_e32 v69, 0, v69
	v_mul_f32_e32 v69, v69, v69
	v_max_f32_e32 v70, 0, v70
	v_mul_f32_e32 v70, v70, v70
	v_max_f32_e32 v71, 0, v71
	v_mul_f32_e32 v71, v71, v71
	v_max_f32_e32 v72, 0, v72
	v_mul_f32_e32 v72, v72, v72
	v_max_f32_e32 v73, 0, v73
	v_mul_f32_e32 v73, v73, v73
	v_max_f32_e32 v74, 0, v74
	v_mul_f32_e32 v74, v74, v74
	v_max_f32_e32 v75, 0, v75
	v_mul_f32_e32 v75, v75, v75
	v_max_f32_e32 v76, 0, v76
	v_mul_f32_e32 v76, v76, v76
	v_max_f32_e32 v77, 0, v77
	v_mul_f32_e32 v77, v77, v77
	v_max_f32_e32 v78, 0, v78
	v_mul_f32_e32 v78, v78, v78
	v_max_f32_e32 v79, 0, v79
	v_mul_f32_e32 v79, v79, v79
	v_max_f32_e32 v80, 0, v80
	v_mul_f32_e32 v80, v80, v80
	v_max_f32_e32 v81, 0, v81
	v_mul_f32_e32 v81, v81, v81
	v_max_f32_e32 v82, 0, v82
	v_mul_f32_e32 v82, v82, v82
	v_max_f32_e32 v83, 0, v83
	v_mul_f32_e32 v83, v83, v83
	v_max_f32_e32 v84, 0, v84
	v_mul_f32_e32 v84, v84, v84
	v_max_f32_e32 v85, 0, v85
	v_mul_f32_e32 v85, v85, v85
	v_max_f32_e32 v86, 0, v86
	v_mul_f32_e32 v86, v86, v86
	v_max_f32_e32 v87, 0, v87
	v_mul_f32_e32 v87, v87, v87
	v_max_f32_e32 v88, 0, v88
	v_mul_f32_e32 v88, v88, v88
	v_max_f32_e32 v89, 0, v89
	v_mul_f32_e32 v89, v89, v89
	v_max_f32_e32 v90, 0, v90
	v_mul_f32_e32 v90, v90, v90
	v_max_f32_e32 v91, 0, v91
	v_mul_f32_e32 v91, v91, v91
	v_max_f32_e32 v92, 0, v92
	v_mul_f32_e32 v92, v92, v92
	v_max_f32_e32 v93, 0, v93
	v_mul_f32_e32 v93, v93, v93
	v_max_f32_e32 v94, 0, v94
	v_mul_f32_e32 v94, v94, v94
	v_max_f32_e32 v95, 0, v95
	v_mul_f32_e32 v95, v95, v95
	v_max_f32_e32 v96, 0, v96
	v_mul_f32_e32 v96, v96, v96
	v_max_f32_e32 v97, 0, v97
	v_mul_f32_e32 v97, v97, v97
	v_max_f32_e32 v98, 0, v98
	v_mul_f32_e32 v98, v98, v98
	v_max_f32_e32 v99, 0, v99
	v_mul_f32_e32 v99, v99, v99
	v_max_f32_e32 v100, 0, v100
	v_mul_f32_e32 v100, v100, v100
	v_max_f32_e32 v101, 0, v101
; template <int EPI> ...
;     ...
;         if (EPI == EPI_FF1) { v0 = fmaxf(v0, 0.f); v1 = fmaxf(v1, 0.f); v0 *= v0; v1 *= v1; }
;         outb[(size_t)row * ldo + c0] = f2bf(v0);
;         outb[(size_t)row * ldo + c1] = f2bf(v1);
	v_mul_f32_e32 v101, v101, v101
	v_max_f32_e32 v102, 0, v102
	v_mul_f32_e32 v102, v102, v102
	v_max_f32_e32 v103, 0, v103
	v_mul_f32_e32 v103, v103, v103
	v_max_f32_e32 v104, 0, v104
	v_mul_f32_e32 v104, v104, v104
	v_max_f32_e32 v105, 0, v105
	v_mul_f32_e32 v105, v105, v105
	v_max_f32_e32 v106, 0, v106
	v_mul_f32_e32 v106, v106, v106
	v_max_f32_e32 v107, 0, v107
	v_mul_f32_e32 v107, v107, v107
	v_max_f32_e32 v108, 0, v108
	v_mul_f32_e32 v108, v108, v108
	v_max_f32_e32 v109, 0, v109
	v_mul_f32_e32 v109, v109, v109
	v_max_f32_e32 v110, 0, v110
	v_mul_f32_e32 v110, v110, v110
	v_max_f32_e32 v111, 0, v111
	v_mul_f32_e32 v111, v111, v111
	v_max_f32_e32 v112, 0, v112
	v_mul_f32_e32 v112, v112, v112
	v_max_f32_e32 v113, 0, v113
	v_mul_f32_e32 v113, v113, v113
	v_max_f32_e32 v114, 0, v114
	v_mul_f32_e32 v114, v114, v114
	v_max_f32_e32 v115, 0, v115
	v_mul_f32_e32 v115, v115, v115
	v_max_f32_e32 v116, 0, v116
	v_mul_f32_e32 v116, v116, v116
	v_max_f32_e32 v117, 0, v117
	v_mul_f32_e32 v117, v117, v117
	v_max_f32_e32 v118, 0, v118
	v_mul_f32_e32 v118, v118, v118
	v_max_f32_e32 v119, 0, v119
	v_mul_f32_e32 v119, v119, v119
	v_max_f32_e32 v120, 0, v120
	v_mul_f32_e32 v120, v120, v120
	v_max_f32_e32 v121, 0, v121
	v_mul_f32_e32 v121, v121, v121
	v_max_f32_e32 v122, 0, v122
	v_mul_f32_e32 v122, v122, v122
	v_max_f32_e32 v123, 0, v123
	v_mul_f32_e32 v123, v123, v123
	v_max_f32_e32 v124, 0, v124
	v_mul_f32_e32 v124, v124, v124
	v_max_f32_e32 v125, 0, v125
	v_mul_f32_e32 v125, v125, v125
	v_max_f32_e32 v126, 0, v126
	v_mul_f32_e32 v126, v126, v126
	v_max_f32_e32 v127, 0, v127
	v_mul_f32_e32 v127, v127, v127
.Lgm_norelu:
	v_cvt_pk_bf16_f32 v0, v0, v1
	v_cvt_pk_bf16_f32 v1, v2, v3
	v_cvt_pk_bf16_f32 v2, v4, v5
	v_cvt_pk_bf16_f32 v3, v6, v7
	s_nop 1
	v_permlane16_swap_b32_e32 v0, v2
	v_permlane16_swap_b32_e32 v1, v3
	global_store_dwordx4 v230, v[0:3], s[22:23]
	v_cvt_pk_bf16_f32 v8, v8, v9
	v_cvt_pk_bf16_f32 v9, v10, v11
	v_cvt_pk_bf16_f32 v10, v12, v13
	v_cvt_pk_bf16_f32 v11, v14, v15
	s_nop 1
	v_permlane16_swap_b32_e32 v8, v10
	v_permlane16_swap_b32_e32 v9, v11
	global_store_dwordx4 v230, v[8:11], s[22:23] offset:64
	v_cvt_pk_bf16_f32 v16, v16, v17
	v_cvt_pk_bf16_f32 v17, v18, v19
	v_cvt_pk_bf16_f32 v18, v20, v21
	v_cvt_pk_bf16_f32 v19, v22, v23
	s_nop 1
	v_permlane16_swap_b32_e32 v16, v18
	v_permlane16_swap_b32_e32 v17, v19
	global_store_dwordx4 v230, v[16:19], s[22:23] offset:128
	v_cvt_pk_bf16_f32 v24, v24, v25
	v_cvt_pk_bf16_f32 v25, v26, v27
	v_cvt_pk_bf16_f32 v26, v28, v29
	v_cvt_pk_bf16_f32 v27, v30, v31
	s_nop 1
	v_permlane16_swap_b32_e32 v24, v26
	v_permlane16_swap_b32_e32 v25, v27
	global_store_dwordx4 v230, v[24:27], s[22:23] offset:192
	v_cvt_pk_bf16_f32 v32, v32, v33
	v_cvt_pk_bf16_f32 v33, v34, v35
	v_cvt_pk_bf16_f32 v34, v36, v37
	v_cvt_pk_bf16_f32 v35, v38, v39
	s_nop 1
	v_permlane16_swap_b32_e32 v32, v34
	v_permlane16_swap_b32_e32 v33, v35
	global_store_dwordx4 v231, v[32:35], s[22:23]
	v_cvt_pk_bf16_f32 v40, v40, v41
	v_cvt_pk_bf16_f32 v41, v42, v43
	v_cvt_pk_bf16_f32 v42, v44, v45
	v_cvt_pk_bf16_f32 v43, v46, v47
	s_nop 1
	v_permlane16_swap_b32_e32 v40, v42
	v_permlane16_swap_b32_e32 v41, v43
	global_store_dwordx4 v231, v[40:43], s[22:23] offset:64
	v_cvt_pk_bf16_f32 v48, v48, v49
	v_cvt_pk_bf16_f32 v49, v50, v51
	v_cvt_pk_bf16_f32 v50, v52, v53
	v_cvt_pk_bf16_f32 v51, v54, v55
	s_nop 1
	v_permlane16_swap_b32_e32 v48, v50
	v_permlane16_swap_b32_e32 v49, v51
	global_store_dwordx4 v231, v[48:51], s[22:23] offset:128
	v_cvt_pk_bf16_f32 v56, v56, v57
	v_cvt_pk_bf16_f32 v57, v58, v59
	v_cvt_pk_bf16_f32 v58, v60, v61
	v_cvt_pk_bf16_f32 v59, v62, v63
	s_nop 1
	v_permlane16_swap_b32_e32 v56, v58
	v_permlane16_swap_b32_e32 v57, v59
	global_store_dwordx4 v231, v[56:59], s[22:23] offset:192
	v_cvt_pk_bf16_f32 v64, v64, v65
	v_cvt_pk_bf16_f32 v65, v66, v67
	v_cvt_pk_bf16_f32 v66, v68, v69
	v_cvt_pk_bf16_f32 v67, v70, v71
	s_nop 1
	v_permlane16_swap_b32_e32 v64, v66
	v_permlane16_swap_b32_e32 v65, v67
	global_store_dwordx4 v232, v[64:67], s[22:23]
	v_cvt_pk_bf16_f32 v72, v72, v73
	v_cvt_pk_bf16_f32 v73, v74, v75
	v_cvt_pk_bf16_f32 v74, v76, v77
	v_cvt_pk_bf16_f32 v75, v78, v79
	s_nop 1
	v_permlane16_swap_b32_e32 v72, v74
	v_permlane16_swap_b32_e32 v73, v75
	global_store_dwordx4 v232, v[72:75], s[22:23] offset:64
	v_cvt_pk_bf16_f32 v80, v80, v81
	v_cvt_pk_bf16_f32 v81, v82, v83
	v_cvt_pk_bf16_f32 v82, v84, v85
	v_cvt_pk_bf16_f32 v83, v86, v87
	s_nop 1
	v_permlane16_swap_b32_e32 v80, v82
	v_permlane16_swap_b32_e32 v81, v83
	global_store_dwordx4 v232, v[80:83], s[22:23] offset:128
	v_cvt_pk_bf16_f32 v88, v88, v89
	v_cvt_pk_bf16_f32 v89, v90, v91
	v_cvt_pk_bf16_f32 v90, v92, v93
	v_cvt_pk_bf16_f32 v91, v94, v95
	s_nop 1
	v_permlane16_swap_b32_e32 v88, v90
	v_permlane16_swap_b32_e32 v89, v91
	global_store_dwordx4 v232, v[88:91], s[22:23] offset:192
	v_cvt_pk_bf16_f32 v96, v96, v97
	v_cvt_pk_bf16_f32 v97, v98, v99
	v_cvt_pk_bf16_f32 v98, v100, v101
	v_cvt_pk_bf16_f32 v99, v102, v103
	s_nop 1
	v_permlane16_swap_b32_e32 v96, v98
	v_permlane16_swap_b32_e32 v97, v99
	global_store_dwordx4 v233, v[96:99], s[22:23]
	v_cvt_pk_bf16_f32 v104, v104, v105
	v_cvt_pk_bf16_f32 v105, v106, v107
	v_cvt_pk_bf16_f32 v106, v108, v109
	v_cvt_pk_bf16_f32 v107, v110, v111
	s_nop 1
	v_permlane16_swap_b32_e32 v104, v106
	v_permlane16_swap_b32_e32 v105, v107
	global_store_dwordx4 v233, v[104:107], s[22:23] offset:64
	v_cvt_pk_bf16_f32 v112, v112, v113
	v_cvt_pk_bf16_f32 v113, v114, v115
	v_cvt_pk_bf16_f32 v114, v116, v117
	v_cvt_pk_bf16_f32 v115, v118, v119
	s_nop 1
	v_permlane16_swap_b32_e32 v112, v114
	v_permlane16_swap_b32_e32 v113, v115
	global_store_dwordx4 v233, v[112:115], s[22:23] offset:128
; template <int EPI> ...
;     ...
;       for (int i = 0; i < 16; i++) {
;         const int rl = rbase + (i & 3) + 8 * (i >> 2);
;         const int row = m0 + rl;
;         float v0 = acc0[i], v1 = acc1[i];
;         if (EPI != EPI_PLAIN) { float rs = sRs[rl]; v0 *= rs; v1 *= rs; }
;         if (EPI == EPI_FF1) { v0 = fmaxf(v0, 0.f); v1 = fmaxf(v1, 0.f); v0 *= v0; v1 *= v1; }
;         outb[(size_t)row * ldo + c0] = f2bf(v0);
;         outb[(size_t)row * ldo + c1] = f2bf(v1);
;       }
; template <int EPI>
; __device__ __forceinline__ void gemm_phase(const Params& p, const u16* __restrict__ A, int lda, const u16* __restrict__ BT, int ldb,
;                            int K, int N, u16* __restrict__ outb, int ldo, int resid_in, int boff) {
;     ...
;     if (EPI == EPI_RES && !part_unit) {
;       const int cc0 = n0 + wn * 64 + (lane & 31);
;       float* xfq = p.out;
; #pragma unroll
;       for (int i = 0; i < 16; i++) {
;         const int row = m0 + wm * 64 + 4 * (lane >> 5) + (i & 3) + 8 * (i >> 2);
;         const float* ra = resid_in ? xrow(p, row) : (xfq + (size_t)row * 1024);
;         const float* rb = resid_in ? xrow(p, row + 32) : (xfq + (size_t)(row + 32) * 1024);
;         acc00[i] = ra[cc0]; acc01[i] = ra[cc0 + 32];
;         acc10[i] = rb[cc0]; acc11[i] = rb[cc0 + 32];
;       }
	v_cvt_pk_bf16_f32 v120, v120, v121
	v_cvt_pk_bf16_f32 v121, v122, v123
	v_cvt_pk_bf16_f32 v122, v124, v125
	v_cvt_pk_bf16_f32 v123, v126, v127
	s_nop 1
	v_permlane16_swap_b32_e32 v120, v122
	v_permlane16_swap_b32_e32 v121, v123
	global_store_dwordx4 v233, v[120:123], s[22:23] offset:192
	v_mov_b64_e32 v[4:5], 0
	v_mov_b64_e32 v[6:7], 0
	v_mov_b64_e32 v[12:13], 0
	v_mov_b64_e32 v[14:15], 0
	v_mov_b64_e32 v[20:21], 0
	v_mov_b64_e32 v[22:23], 0
	v_mov_b64_e32 v[28:29], 0
	v_mov_b64_e32 v[30:31], 0
	v_mov_b64_e32 v[36:37], 0
	v_mov_b64_e32 v[38:39], 0
	v_mov_b64_e32 v[44:45], 0
	v_mov_b64_e32 v[46:47], 0
	v_mov_b64_e32 v[52:53], 0
	v_mov_b64_e32 v[54:55], 0
	v_mov_b64_e32 v[60:61], 0
	v_mov_b64_e32 v[62:63], 0
	v_mov_b64_e32 v[68:69], 0
	v_mov_b64_e32 v[70:71], 0
	v_mov_b64_e32 v[76:77], 0
	v_mov_b64_e32 v[78:79], 0
	v_mov_b64_e32 v[84:85], 0
	v_mov_b64_e32 v[86:87], 0
	v_mov_b64_e32 v[92:93], 0
	v_mov_b64_e32 v[94:95], 0
	v_mov_b64_e32 v[100:101], 0
	v_mov_b64_e32 v[102:103], 0
	v_mov_b64_e32 v[108:109], 0
	v_mov_b64_e32 v[110:111], 0
	v_mov_b64_e32 v[116:117], 0
	v_mov_b64_e32 v[118:119], 0
	v_mov_b64_e32 v[124:125], 0
	v_mov_b64_e32 v[126:127], 0
	v_mov_b64_e32 v[178:179], 0
	v_mov_b64_e32 v[180:181], 0
	v_mov_b64_e32 v[182:183], 0
	v_mov_b64_e32 v[184:185], 0
	v_mov_b64_e32 v[186:187], 0
	v_mov_b64_e32 v[188:189], 0
	v_mov_b64_e32 v[190:191], 0
	v_mov_b64_e32 v[192:193], 0
	v_mov_b64_e32 v[194:195], 0
	v_mov_b64_e32 v[196:197], 0
	v_mov_b64_e32 v[198:199], 0
	v_mov_b64_e32 v[200:201], 0
	v_mov_b64_e32 v[202:203], 0
	v_mov_b64_e32 v[204:205], 0
	v_mov_b64_e32 v[206:207], 0
	v_mov_b64_e32 v[208:209], 0
	v_mov_b64_e32 v[210:211], 0
	v_mov_b64_e32 v[212:213], 0
	v_mov_b64_e32 v[214:215], 0
	v_mov_b64_e32 v[216:217], 0
	v_mov_b64_e32 v[218:219], 0
	v_mov_b64_e32 v[220:221], 0
	v_mov_b64_e32 v[222:223], 0
	v_mov_b64_e32 v[224:225], 0
	v_mov_b64_e32 v[0:1], 0
	v_mov_b64_e32 v[2:3], 0
	v_mov_b64_e32 v[8:9], 0
	v_mov_b64_e32 v[10:11], 0
	v_mov_b64_e32 v[16:17], 0
	v_mov_b64_e32 v[18:19], 0
	v_mov_b64_e32 v[24:25], 0
	v_mov_b64_e32 v[26:27], 0
	v_mov_b64_e32 v[32:33], 0
	v_mov_b64_e32 v[34:35], 0
	v_mov_b64_e32 v[40:41], 0
	v_mov_b64_e32 v[42:43], 0
	v_mov_b64_e32 v[48:49], 0
	v_mov_b64_e32 v[50:51], 0
	v_mov_b64_e32 v[56:57], 0
	v_mov_b64_e32 v[58:59], 0
	v_mov_b64_e32 v[64:65], 0
	v_mov_b64_e32 v[66:67], 0
	v_mov_b64_e32 v[72:73], 0
	v_mov_b64_e32 v[74:75], 0
	v_mov_b64_e32 v[80:81], 0
	v_mov_b64_e32 v[82:83], 0
	v_mov_b64_e32 v[88:89], 0
	v_mov_b64_e32 v[90:91], 0
	v_mov_b64_e32 v[96:97], 0
	v_mov_b64_e32 v[98:99], 0
	v_mov_b64_e32 v[104:105], 0
	v_mov_b64_e32 v[106:107], 0
	v_mov_b64_e32 v[112:113], 0
	v_mov_b64_e32 v[114:115], 0
	v_mov_b64_e32 v[120:121], 0
	v_mov_b64_e32 v[122:123], 0
	s_xor_b32 s33, s33, 0x400
	s_branch .Lgc_next
.Lgc_epi_res:
	s_lshl_b32 s11, s6, 8
	s_lshl_b32 s12, s4, 6
	s_add_u32 s11, s11, s12
	v_add_u32_e32 v238, s11, v248
	v_lshlrev_b32_e32 v243, 12, v238
	s_lshl_b32 s11, s7, 7
	v_lshl_add_u32 v239, v249, 2, s11
	v_lshlrev_b32_e32 v239, 2, v239
	v_add_u32_e32 v243, v243, v239
	v_add_u32_e32 v244, 0x10000, v243
	v_add_u32_e32 v245, 0x10000, v244
	v_add_u32_e32 v246, 0x10000, v245
	v_lshlrev_b32_e32 v247, 6, v238
	s_lshl_b32 s11, s7, 3
	v_add_u32_e32 v247, s11, v247
	s_lshl_b32 s11, s6, 8
	s_lshl_b32 s12, s4, 6
	s_add_u32 s11, s11, s12
	v_add_u32_e32 v238, s11, v248
	v_mul_lo_u32 v230, v238, s24
	s_lshl_b32 s11, s7, 7
	v_and_b32_e32 v239, 1, v249
	v_lshrrev_b32_e32 v240, 1, v249
	v_lshlrev_b32_e32 v239, 4, v239
	v_lshl_add_u32 v239, v240, 3, v239
	v_add_u32_e32 v239, s11, v239
	v_lshlrev_b32_e32 v239, 1, v239
	v_add_u32_e32 v230, v230, v239
	s_lshl_b32 s11, s24, 4
	v_add_u32_e32 v231, s11, v230
	v_add_u32_e32 v232, s11, v231
	v_add_u32_e32 v233, s11, v232
	global_load_dwordx4 v[130:133], v243, s[48:49]
	global_load_dwordx4 v[134:137], v243, s[48:49] offset:64
	global_load_dwordx4 v[138:141], v243, s[48:49] offset:128
	global_load_dwordx4 v[142:145], v243, s[48:49] offset:192
	global_load_dwordx4 v[146:149], v243, s[48:49] offset:256
	global_load_dwordx4 v[150:153], v243, s[48:49] offset:320
	global_load_dwordx4 v[154:157], v243, s[48:49] offset:384
	global_load_dwordx4 v[158:161], v243, s[48:49] offset:448
	global_load_dwordx4 v[162:165], v244, s[48:49]
	global_load_dwordx4 v[166:169], v244, s[48:49] offset:64
	global_load_dwordx4 v[170:173], v244, s[48:49] offset:128
	global_load_dwordx4 v[174:177], v244, s[48:49] offset:192
	global_load_dwordx4 v[178:181], v244, s[48:49] offset:256
	global_load_dwordx4 v[182:185], v244, s[48:49] offset:320
	global_load_dwordx4 v[186:189], v244, s[48:49] offset:384
	global_load_dwordx4 v[190:193], v244, s[48:49] offset:448
	global_load_dwordx4 v[194:197], v245, s[48:49]
	global_load_dwordx4 v[198:201], v245, s[48:49] offset:64
	global_load_dwordx4 v[202:205], v245, s[48:49] offset:128
	global_load_dwordx4 v[206:209], v245, s[48:49] offset:192
	global_load_dwordx4 v[210:213], v245, s[48:49] offset:256
	global_load_dwordx4 v[214:217], v245, s[48:49] offset:320
	global_load_dwordx4 v[218:221], v245, s[48:49] offset:384
	global_load_dwordx4 v[222:225], v245, s[48:49] offset:448
	s_waitcnt vmcnt(23)
	v_add_f32_e32 v0, v0, v130
	v_add_f32_e32 v1, v1, v131
	v_add_f32_e32 v2, v2, v132
	v_add_f32_e32 v3, v3, v133
	global_load_dwordx4 v[130:133], v246, s[48:49]
	s_waitcnt vmcnt(23)
	v_add_f32_e32 v4, v4, v134
	v_add_f32_e32 v5, v5, v135
	v_add_f32_e32 v6, v6, v136
	v_add_f32_e32 v7, v7, v137
	global_load_dwordx4 v[134:137], v246, s[48:49] offset:64
	s_waitcnt vmcnt(23)
	v_add_f32_e32 v8, v8, v138
	v_add_f32_e32 v9, v9, v139
	v_add_f32_e32 v10, v10, v140
	v_add_f32_e32 v11, v11, v141
	global_load_dwordx4 v[138:141], v246, s[48:49] offset:128
	s_waitcnt vmcnt(23)
; template <int EPI>
; __device__ __forceinline__ void gemm_phase(const Params& p, const u16* __restrict__ A, int lda, const u16* __restrict__ BT, int ldb,
;                            int K, int N, u16* __restrict__ outb, int ldo, int resid_in, int boff) {
;     ...
;     if (EPI == EPI_RES && !part_unit) {
;       const int cc0 = n0 + wn * 64 + (lane & 31);
;       float* xfq = p.out;
; #pragma unroll
;       for (int i = 0; i < 16; i++) {
;         const int row = m0 + wm * 64 + 4 * (lane >> 5) + (i & 3) + 8 * (i >> 2);
;         const float* ra = resid_in ? xrow(p, row) : (xfq + (size_t)row * 1024);
;         const float* rb = resid_in ? xrow(p, row + 32) : (xfq + (size_t)(row + 32) * 1024);
;         acc00[i] = ra[cc0]; acc01[i] = ra[cc0 + 32];
;         acc10[i] = rb[cc0]; acc11[i] = rb[cc0 + 32];
;       }
	v_add_f32_e32 v12, v12, v142
	v_add_f32_e32 v13, v13, v143
	v_add_f32_e32 v14, v14, v144
	v_add_f32_e32 v15, v15, v145
	global_load_dwordx4 v[142:145], v246, s[48:49] offset:192
	s_waitcnt vmcnt(23)
	v_add_f32_e32 v16, v16, v146
	v_add_f32_e32 v17, v17, v147
	v_add_f32_e32 v18, v18, v148
	v_add_f32_e32 v19, v19, v149
	global_load_dwordx4 v[146:149], v246, s[48:49] offset:256
	s_waitcnt vmcnt(23)
	v_add_f32_e32 v20, v20, v150
	v_add_f32_e32 v21, v21, v151
	v_add_f32_e32 v22, v22, v152
	v_add_f32_e32 v23, v23, v153
	global_load_dwordx4 v[150:153], v246, s[48:49] offset:320
	s_waitcnt vmcnt(23)
	v_add_f32_e32 v24, v24, v154
	v_add_f32_e32 v25, v25, v155
	v_add_f32_e32 v26, v26, v156
	v_add_f32_e32 v27, v27, v157
	global_load_dwordx4 v[154:157], v246, s[48:49] offset:384
	s_waitcnt vmcnt(23)
	v_add_f32_e32 v28, v28, v158
	v_add_f32_e32 v29, v29, v159
	v_add_f32_e32 v30, v30, v160
	v_add_f32_e32 v31, v31, v161
	global_load_dwordx4 v[158:161], v246, s[48:49] offset:448
	s_waitcnt vmcnt(23)
	v_add_f32_e32 v32, v32, v162
	v_add_f32_e32 v33, v33, v163
	v_add_f32_e32 v34, v34, v164
	v_add_f32_e32 v35, v35, v165
	s_waitcnt vmcnt(22)
	v_add_f32_e32 v36, v36, v166
	v_add_f32_e32 v37, v37, v167
	v_add_f32_e32 v38, v38, v168
	v_add_f32_e32 v39, v39, v169
	s_waitcnt vmcnt(21)
	v_add_f32_e32 v40, v40, v170
	v_add_f32_e32 v41, v41, v171
	v_add_f32_e32 v42, v42, v172
	v_add_f32_e32 v43, v43, v173
	s_waitcnt vmcnt(20)
	v_add_f32_e32 v44, v44, v174
	v_add_f32_e32 v45, v45, v175
	v_add_f32_e32 v46, v46, v176
	v_add_f32_e32 v47, v47, v177
	s_waitcnt vmcnt(19)
	v_add_f32_e32 v48, v48, v178
	v_add_f32_e32 v49, v49, v179
	v_add_f32_e32 v50, v50, v180
	v_add_f32_e32 v51, v51, v181
	s_waitcnt vmcnt(18)
	v_add_f32_e32 v52, v52, v182
	v_add_f32_e32 v53, v53, v183
	v_add_f32_e32 v54, v54, v184
	v_add_f32_e32 v55, v55, v185
	s_waitcnt vmcnt(17)
	v_add_f32_e32 v56, v56, v186
	v_add_f32_e32 v57, v57, v187
	v_add_f32_e32 v58, v58, v188
	v_add_f32_e32 v59, v59, v189
	s_waitcnt vmcnt(16)
	v_add_f32_e32 v60, v60, v190
	v_add_f32_e32 v61, v61, v191
	v_add_f32_e32 v62, v62, v192
	v_add_f32_e32 v63, v63, v193
	s_waitcnt vmcnt(15)
	v_add_f32_e32 v64, v64, v194
	v_add_f32_e32 v65, v65, v195
	v_add_f32_e32 v66, v66, v196
	v_add_f32_e32 v67, v67, v197
	s_waitcnt vmcnt(14)
	v_add_f32_e32 v68, v68, v198
	v_add_f32_e32 v69, v69, v199
	v_add_f32_e32 v70, v70, v200
	v_add_f32_e32 v71, v71, v201
	s_waitcnt vmcnt(13)
	v_add_f32_e32 v72, v72, v202
	v_add_f32_e32 v73, v73, v203
	v_add_f32_e32 v74, v74, v204
	v_add_f32_e32 v75, v75, v205
	s_waitcnt vmcnt(12)
	v_add_f32_e32 v76, v76, v206
	v_add_f32_e32 v77, v77, v207
	v_add_f32_e32 v78, v78, v208
	v_add_f32_e32 v79, v79, v209
	s_waitcnt vmcnt(11)
	v_add_f32_e32 v80, v80, v210
	v_add_f32_e32 v81, v81, v211
	v_add_f32_e32 v82, v82, v212
	v_add_f32_e32 v83, v83, v213
	s_waitcnt vmcnt(10)
	v_add_f32_e32 v84, v84, v214
	v_add_f32_e32 v85, v85, v215
	v_add_f32_e32 v86, v86, v216
	v_add_f32_e32 v87, v87, v217
	s_waitcnt vmcnt(9)
	v_add_f32_e32 v88, v88, v218
	v_add_f32_e32 v89, v89, v219
	v_add_f32_e32 v90, v90, v220
	v_add_f32_e32 v91, v91, v221
	s_waitcnt vmcnt(8)
	v_add_f32_e32 v92, v92, v222
	v_add_f32_e32 v93, v93, v223
	v_add_f32_e32 v94, v94, v224
	v_add_f32_e32 v95, v95, v225
	s_waitcnt vmcnt(7)
	v_add_f32_e32 v96, v96, v130
	v_add_f32_e32 v97, v97, v131
	v_add_f32_e32 v98, v98, v132
	v_add_f32_e32 v99, v99, v133
	s_waitcnt vmcnt(6)
	v_add_f32_e32 v100, v100, v134
	v_add_f32_e32 v101, v101, v135
	v_add_f32_e32 v102, v102, v136
	v_add_f32_e32 v103, v103, v137
	s_waitcnt vmcnt(5)
	v_add_f32_e32 v104, v104, v138
	v_add_f32_e32 v105, v105, v139
	v_add_f32_e32 v106, v106, v140
	v_add_f32_e32 v107, v107, v141
	s_waitcnt vmcnt(4)
	v_add_f32_e32 v108, v108, v142
	v_add_f32_e32 v109, v109, v143
	v_add_f32_e32 v110, v110, v144
	v_add_f32_e32 v111, v111, v145
	s_waitcnt vmcnt(3)
	v_add_f32_e32 v112, v112, v146
	v_add_f32_e32 v113, v113, v147
	v_add_f32_e32 v114, v114, v148
	v_add_f32_e32 v115, v115, v149
	s_waitcnt vmcnt(2)
	v_add_f32_e32 v116, v116, v150
	v_add_f32_e32 v117, v117, v151
	v_add_f32_e32 v118, v118, v152
	v_add_f32_e32 v119, v119, v153
	s_waitcnt vmcnt(1)
	v_add_f32_e32 v120, v120, v154
	v_add_f32_e32 v121, v121, v155
	v_add_f32_e32 v122, v122, v156
	v_add_f32_e32 v123, v123, v157
	s_waitcnt vmcnt(0)
; template <int EPI> ...
;     ...
;       for (int i = 0; i < 16; i++) {
;         const int rl = rbase + (i & 3) + 8 * (i >> 2);
;         const int row = m0 + rl;
;         float v0 = acc0[i], v1 = acc1[i];
;         xf[(size_t)row * 1024 + c0] = v0;
;         xf[(size_t)row * 1024 + c1] = v1;
;         outb[(size_t)row * 1024 + c0] = f2bf(v0);
;         outb[(size_t)row * 1024 + c1] = f2bf(v1);
;         float s = hsum32(v0 * v0 + v1 * v1);
;         if ((lane & 31) == 0) part[(size_t)row * 16 + nt * 2 + wn] = s;
	v_add_f32_e32 v124, v124, v158
	v_add_f32_e32 v125, v125, v159
	v_add_f32_e32 v126, v126, v160
	v_add_f32_e32 v127, v127, v161
	global_store_dwordx4 v243, v[0:3], s[94:95]
	v_mul_f32_e32 v234, v0, v0
	v_fmac_f32_e32 v234, v1, v1
	v_fmac_f32_e32 v234, v2, v2
	v_fmac_f32_e32 v234, v3, v3
	global_store_dwordx4 v243, v[4:7], s[94:95] offset:64
	v_fmac_f32_e32 v234, v4, v4
	v_fmac_f32_e32 v234, v5, v5
	v_fmac_f32_e32 v234, v6, v6
	v_fmac_f32_e32 v234, v7, v7
	global_store_dwordx4 v243, v[8:11], s[94:95] offset:128
	v_fmac_f32_e32 v234, v8, v8
	v_fmac_f32_e32 v234, v9, v9
	v_fmac_f32_e32 v234, v10, v10
	v_fmac_f32_e32 v234, v11, v11
	global_store_dwordx4 v243, v[12:15], s[94:95] offset:192
	v_fmac_f32_e32 v234, v12, v12
	v_fmac_f32_e32 v234, v13, v13
	v_fmac_f32_e32 v234, v14, v14
	v_fmac_f32_e32 v234, v15, v15
	global_store_dwordx4 v243, v[16:19], s[94:95] offset:256
	v_fmac_f32_e32 v234, v16, v16
	v_fmac_f32_e32 v234, v17, v17
	v_fmac_f32_e32 v234, v18, v18
	v_fmac_f32_e32 v234, v19, v19
	global_store_dwordx4 v243, v[20:23], s[94:95] offset:320
	v_fmac_f32_e32 v234, v20, v20
	v_fmac_f32_e32 v234, v21, v21
	v_fmac_f32_e32 v234, v22, v22
	v_fmac_f32_e32 v234, v23, v23
	global_store_dwordx4 v243, v[24:27], s[94:95] offset:384
	v_fmac_f32_e32 v234, v24, v24
	v_fmac_f32_e32 v234, v25, v25
	v_fmac_f32_e32 v234, v26, v26
	v_fmac_f32_e32 v234, v27, v27
	global_store_dwordx4 v243, v[28:31], s[94:95] offset:448
	v_fmac_f32_e32 v234, v28, v28
	v_fmac_f32_e32 v234, v29, v29
	v_fmac_f32_e32 v234, v30, v30
	v_fmac_f32_e32 v234, v31, v31
	global_store_dwordx4 v244, v[32:35], s[94:95]
	v_mul_f32_e32 v235, v32, v32
	v_fmac_f32_e32 v235, v33, v33
	v_fmac_f32_e32 v235, v34, v34
	v_fmac_f32_e32 v235, v35, v35
	global_store_dwordx4 v244, v[36:39], s[94:95] offset:64
	v_fmac_f32_e32 v235, v36, v36
	v_fmac_f32_e32 v235, v37, v37
	v_fmac_f32_e32 v235, v38, v38
	v_fmac_f32_e32 v235, v39, v39
	global_store_dwordx4 v244, v[40:43], s[94:95] offset:128
	v_fmac_f32_e32 v235, v40, v40
	v_fmac_f32_e32 v235, v41, v41
	v_fmac_f32_e32 v235, v42, v42
	v_fmac_f32_e32 v235, v43, v43
	global_store_dwordx4 v244, v[44:47], s[94:95] offset:192
	v_fmac_f32_e32 v235, v44, v44
	v_fmac_f32_e32 v235, v45, v45
	v_fmac_f32_e32 v235, v46, v46
	v_fmac_f32_e32 v235, v47, v47
	global_store_dwordx4 v244, v[48:51], s[94:95] offset:256
	v_fmac_f32_e32 v235, v48, v48
	v_fmac_f32_e32 v235, v49, v49
	v_fmac_f32_e32 v235, v50, v50
	v_fmac_f32_e32 v235, v51, v51
	global_store_dwordx4 v244, v[52:55], s[94:95] offset:320
	v_fmac_f32_e32 v235, v52, v52
	v_fmac_f32_e32 v235, v53, v53
	v_fmac_f32_e32 v235, v54, v54
	v_fmac_f32_e32 v235, v55, v55
	global_store_dwordx4 v244, v[56:59], s[94:95] offset:384
	v_fmac_f32_e32 v235, v56, v56
	v_fmac_f32_e32 v235, v57, v57
	v_fmac_f32_e32 v235, v58, v58
	v_fmac_f32_e32 v235, v59, v59
	global_store_dwordx4 v244, v[60:63], s[94:95] offset:448
	v_fmac_f32_e32 v235, v60, v60
	v_fmac_f32_e32 v235, v61, v61
	v_fmac_f32_e32 v235, v62, v62
	v_fmac_f32_e32 v235, v63, v63
	global_store_dwordx4 v245, v[64:67], s[94:95]
	v_mul_f32_e32 v236, v64, v64
	v_fmac_f32_e32 v236, v65, v65
	v_fmac_f32_e32 v236, v66, v66
	v_fmac_f32_e32 v236, v67, v67
	global_store_dwordx4 v245, v[68:71], s[94:95] offset:64
	v_fmac_f32_e32 v236, v68, v68
	v_fmac_f32_e32 v236, v69, v69
	v_fmac_f32_e32 v236, v70, v70
	v_fmac_f32_e32 v236, v71, v71
	global_store_dwordx4 v245, v[72:75], s[94:95] offset:128
	v_fmac_f32_e32 v236, v72, v72
	v_fmac_f32_e32 v236, v73, v73
	v_fmac_f32_e32 v236, v74, v74
	v_fmac_f32_e32 v236, v75, v75
	global_store_dwordx4 v245, v[76:79], s[94:95] offset:192
	v_fmac_f32_e32 v236, v76, v76
	v_fmac_f32_e32 v236, v77, v77
	v_fmac_f32_e32 v236, v78, v78
	v_fmac_f32_e32 v236, v79, v79
	global_store_dwordx4 v245, v[80:83], s[94:95] offset:256
	v_fmac_f32_e32 v236, v80, v80
	v_fmac_f32_e32 v236, v81, v81
	v_fmac_f32_e32 v236, v82, v82
	v_fmac_f32_e32 v236, v83, v83
	global_store_dwordx4 v245, v[84:87], s[94:95] offset:320
	v_fmac_f32_e32 v236, v84, v84
	v_fmac_f32_e32 v236, v85, v85
	v_fmac_f32_e32 v236, v86, v86
	v_fmac_f32_e32 v236, v87, v87
	global_store_dwordx4 v245, v[88:91], s[94:95] offset:384
	v_fmac_f32_e32 v236, v88, v88
	v_fmac_f32_e32 v236, v89, v89
	v_fmac_f32_e32 v236, v90, v90
	v_fmac_f32_e32 v236, v91, v91
	global_store_dwordx4 v245, v[92:95], s[94:95] offset:448
	v_fmac_f32_e32 v236, v92, v92
	v_fmac_f32_e32 v236, v93, v93
	v_fmac_f32_e32 v236, v94, v94
	v_fmac_f32_e32 v236, v95, v95
	global_store_dwordx4 v246, v[96:99], s[94:95]
	v_mul_f32_e32 v237, v96, v96
	v_fmac_f32_e32 v237, v97, v97
	v_fmac_f32_e32 v237, v98, v98
	v_fmac_f32_e32 v237, v99, v99
	global_store_dwordx4 v246, v[100:103], s[94:95] offset:64
	v_fmac_f32_e32 v237, v100, v100
	v_fmac_f32_e32 v237, v101, v101
	v_fmac_f32_e32 v237, v102, v102
	v_fmac_f32_e32 v237, v103, v103
	global_store_dwordx4 v246, v[104:107], s[94:95] offset:128
	v_fmac_f32_e32 v237, v104, v104
	v_fmac_f32_e32 v237, v105, v105
	v_fmac_f32_e32 v237, v106, v106
	v_fmac_f32_e32 v237, v107, v107
	global_store_dwordx4 v246, v[108:111], s[94:95] offset:192
	v_fmac_f32_e32 v237, v108, v108
	v_fmac_f32_e32 v237, v109, v109
	v_fmac_f32_e32 v237, v110, v110
	v_fmac_f32_e32 v237, v111, v111
	global_store_dwordx4 v246, v[112:115], s[94:95] offset:256
	v_fmac_f32_e32 v237, v112, v112
	v_fmac_f32_e32 v237, v113, v113
	v_fmac_f32_e32 v237, v114, v114
	v_fmac_f32_e32 v237, v115, v115
	global_store_dwordx4 v246, v[116:119], s[94:95] offset:320
	v_fmac_f32_e32 v237, v116, v116
	v_fmac_f32_e32 v237, v117, v117
	v_fmac_f32_e32 v237, v118, v118
	v_fmac_f32_e32 v237, v119, v119
	global_store_dwordx4 v246, v[120:123], s[94:95] offset:384
	v_fmac_f32_e32 v237, v120, v120
; template <int EPI> ...
;     ...
;       for (int i = 0; i < 16; i++) {
;         const int rl = rbase + (i & 3) + 8 * (i >> 2);
;         const int row = m0 + rl;
;         float v0 = acc0[i], v1 = acc1[i];
;         xf[(size_t)row * 1024 + c0] = v0;
;         xf[(size_t)row * 1024 + c1] = v1;
;         outb[(size_t)row * 1024 + c0] = f2bf(v0);
;         outb[(size_t)row * 1024 + c1] = f2bf(v1);
;         float s = hsum32(v0 * v0 + v1 * v1);
;         if ((lane & 31) == 0) part[(size_t)row * 16 + nt * 2 + wn] = s;
	v_fmac_f32_e32 v237, v121, v121
	v_fmac_f32_e32 v237, v122, v122
	v_fmac_f32_e32 v237, v123, v123
	global_store_dwordx4 v246, v[124:127], s[94:95] offset:448
	v_fmac_f32_e32 v237, v124, v124
	v_fmac_f32_e32 v237, v125, v125
	v_fmac_f32_e32 v237, v126, v126
	v_fmac_f32_e32 v237, v127, v127
	v_cvt_pk_bf16_f32 v0, v0, v1
	v_cvt_pk_bf16_f32 v1, v2, v3
	v_cvt_pk_bf16_f32 v2, v4, v5
	v_cvt_pk_bf16_f32 v3, v6, v7
	s_nop 1
	v_permlane16_swap_b32_e32 v0, v2
	v_permlane16_swap_b32_e32 v1, v3
	global_store_dwordx4 v230, v[0:3], s[22:23]
	v_cvt_pk_bf16_f32 v8, v8, v9
	v_cvt_pk_bf16_f32 v9, v10, v11
	v_cvt_pk_bf16_f32 v10, v12, v13
	v_cvt_pk_bf16_f32 v11, v14, v15
	s_nop 1
	v_permlane16_swap_b32_e32 v8, v10
	v_permlane16_swap_b32_e32 v9, v11
	global_store_dwordx4 v230, v[8:11], s[22:23] offset:64
	v_cvt_pk_bf16_f32 v16, v16, v17
	v_cvt_pk_bf16_f32 v17, v18, v19
	v_cvt_pk_bf16_f32 v18, v20, v21
	v_cvt_pk_bf16_f32 v19, v22, v23
	s_nop 1
	v_permlane16_swap_b32_e32 v16, v18
	v_permlane16_swap_b32_e32 v17, v19
	global_store_dwordx4 v230, v[16:19], s[22:23] offset:128
	v_cvt_pk_bf16_f32 v24, v24, v25
	v_cvt_pk_bf16_f32 v25, v26, v27
	v_cvt_pk_bf16_f32 v26, v28, v29
	v_cvt_pk_bf16_f32 v27, v30, v31
	s_nop 1
	v_permlane16_swap_b32_e32 v24, v26
	v_permlane16_swap_b32_e32 v25, v27
	global_store_dwordx4 v230, v[24:27], s[22:23] offset:192
	v_cvt_pk_bf16_f32 v32, v32, v33
	v_cvt_pk_bf16_f32 v33, v34, v35
	v_cvt_pk_bf16_f32 v34, v36, v37
	v_cvt_pk_bf16_f32 v35, v38, v39
	s_nop 1
	v_permlane16_swap_b32_e32 v32, v34
	v_permlane16_swap_b32_e32 v33, v35
	global_store_dwordx4 v231, v[32:35], s[22:23]
	v_cvt_pk_bf16_f32 v40, v40, v41
	v_cvt_pk_bf16_f32 v41, v42, v43
	v_cvt_pk_bf16_f32 v42, v44, v45
	v_cvt_pk_bf16_f32 v43, v46, v47
	s_nop 1
	v_permlane16_swap_b32_e32 v40, v42
	v_permlane16_swap_b32_e32 v41, v43
	global_store_dwordx4 v231, v[40:43], s[22:23] offset:64
	v_cvt_pk_bf16_f32 v48, v48, v49
	v_cvt_pk_bf16_f32 v49, v50, v51
	v_cvt_pk_bf16_f32 v50, v52, v53
	v_cvt_pk_bf16_f32 v51, v54, v55
	s_nop 1
	v_permlane16_swap_b32_e32 v48, v50
	v_permlane16_swap_b32_e32 v49, v51
	global_store_dwordx4 v231, v[48:51], s[22:23] offset:128
	v_cvt_pk_bf16_f32 v56, v56, v57
	v_cvt_pk_bf16_f32 v57, v58, v59
	v_cvt_pk_bf16_f32 v58, v60, v61
	v_cvt_pk_bf16_f32 v59, v62, v63
	s_nop 1
	v_permlane16_swap_b32_e32 v56, v58
	v_permlane16_swap_b32_e32 v57, v59
	global_store_dwordx4 v231, v[56:59], s[22:23] offset:192
	v_cvt_pk_bf16_f32 v64, v64, v65
	v_cvt_pk_bf16_f32 v65, v66, v67
	v_cvt_pk_bf16_f32 v66, v68, v69
	v_cvt_pk_bf16_f32 v67, v70, v71
	s_nop 1
	v_permlane16_swap_b32_e32 v64, v66
	v_permlane16_swap_b32_e32 v65, v67
	global_store_dwordx4 v232, v[64:67], s[22:23]
	v_cvt_pk_bf16_f32 v72, v72, v73
	v_cvt_pk_bf16_f32 v73, v74, v75
	v_cvt_pk_bf16_f32 v74, v76, v77
	v_cvt_pk_bf16_f32 v75, v78, v79
	s_nop 1
	v_permlane16_swap_b32_e32 v72, v74
	v_permlane16_swap_b32_e32 v73, v75
	global_store_dwordx4 v232, v[72:75], s[22:23] offset:64
	v_cvt_pk_bf16_f32 v80, v80, v81
	v_cvt_pk_bf16_f32 v81, v82, v83
	v_cvt_pk_bf16_f32 v82, v84, v85
	v_cvt_pk_bf16_f32 v83, v86, v87
	s_nop 1
	v_permlane16_swap_b32_e32 v80, v82
	v_permlane16_swap_b32_e32 v81, v83
	global_store_dwordx4 v232, v[80:83], s[22:23] offset:128
	v_cvt_pk_bf16_f32 v88, v88, v89
	v_cvt_pk_bf16_f32 v89, v90, v91
	v_cvt_pk_bf16_f32 v90, v92, v93
	v_cvt_pk_bf16_f32 v91, v94, v95
	s_nop 1
	v_permlane16_swap_b32_e32 v88, v90
	v_permlane16_swap_b32_e32 v89, v91
	global_store_dwordx4 v232, v[88:91], s[22:23] offset:192
	v_cvt_pk_bf16_f32 v96, v96, v97
	v_cvt_pk_bf16_f32 v97, v98, v99
	v_cvt_pk_bf16_f32 v98, v100, v101
	v_cvt_pk_bf16_f32 v99, v102, v103
	s_nop 1
	v_permlane16_swap_b32_e32 v96, v98
	v_permlane16_swap_b32_e32 v97, v99
	global_store_dwordx4 v233, v[96:99], s[22:23]
	v_cvt_pk_bf16_f32 v104, v104, v105
	v_cvt_pk_bf16_f32 v105, v106, v107
	v_cvt_pk_bf16_f32 v106, v108, v109
	v_cvt_pk_bf16_f32 v107, v110, v111
	s_nop 1
	v_permlane16_swap_b32_e32 v104, v106
	v_permlane16_swap_b32_e32 v105, v107
	global_store_dwordx4 v233, v[104:107], s[22:23] offset:64
	v_cvt_pk_bf16_f32 v112, v112, v113
	v_cvt_pk_bf16_f32 v113, v114, v115
	v_cvt_pk_bf16_f32 v114, v116, v117
	v_cvt_pk_bf16_f32 v115, v118, v119
	s_nop 1
	v_permlane16_swap_b32_e32 v112, v114
	v_permlane16_swap_b32_e32 v113, v115
	global_store_dwordx4 v233, v[112:115], s[22:23] offset:128
	v_cvt_pk_bf16_f32 v120, v120, v121
	v_cvt_pk_bf16_f32 v121, v122, v123
	v_cvt_pk_bf16_f32 v122, v124, v125
	v_cvt_pk_bf16_f32 v123, v126, v127
	s_nop 1
	v_permlane16_swap_b32_e32 v120, v122
	v_permlane16_swap_b32_e32 v121, v123
	global_store_dwordx4 v233, v[120:123], s[22:23] offset:192
	v_mov_b32_e32 v238, v234
	v_mov_b32_e32 v239, v235
	v_mov_b32_e32 v240, v236
	v_mov_b32_e32 v241, v237
	s_nop 1
	v_permlane16_swap_b32_e32 v238, v234
	v_permlane16_swap_b32_e32 v239, v235
	v_permlane16_swap_b32_e32 v240, v236
	v_permlane16_swap_b32_e32 v241, v237
	v_add_f32_e32 v234, v234, v238
	v_add_f32_e32 v235, v235, v239
	v_add_f32_e32 v236, v236, v240
	v_add_f32_e32 v237, v237, v241
	v_mov_b32_e32 v238, v234
	v_mov_b32_e32 v239, v235
	v_mov_b32_e32 v240, v236
	v_mov_b32_e32 v241, v237
	s_nop 1
	v_permlane32_swap_b32_e32 v238, v234
	v_permlane32_swap_b32_e32 v239, v235
	v_permlane32_swap_b32_e32 v240, v236
	v_permlane32_swap_b32_e32 v241, v237
	v_add_f32_e32 v234, v234, v238
	v_add_f32_e32 v235, v235, v239
	v_add_f32_e32 v236, v236, v240
	v_add_f32_e32 v237, v237, v241
	v_mov_b32_e32 v238, v234
	v_mov_b32_e32 v239, 0
	global_store_dwordx2 v247, v[238:239], s[14:15]
	s_nop 1
	v_mov_b32_e32 v238, v235
	v_mov_b32_e32 v239, 0
	global_store_dwordx2 v247, v[238:239], s[14:15] offset:1024
	s_nop 1
	v_mov_b32_e32 v238, v236
; #define RAW_BARRIER() do { asm volatile("s_waitcnt lgkmcnt(0)" ::: "memory"); __builtin_amdgcn_s_barrier(); asm volatile("" ::: "memory"); } while (0)
; template <int EPI>
; __device__ __forceinline__ void gemm_phase(const Params& p, const u16* __restrict__ A, int lda, const u16* __restrict__ BT, int ldb,
;                            int K, int N, u16* __restrict__ outb, int ldo, int resid_in, int boff) {
;     ...
;     LOADX(0);
;     if (KT > 1) LOADY(1);
;     f32x16 acc00, acc01, acc10, acc11;
;     if (EPI == EPI_RES && !part_unit) {
;       const int cc0 = n0 + wn * 64 + (lane & 31);
;       float* xfq = p.out;
; #pragma unroll
;       for (int i = 0; i < 16; i++) {
;         const int row = m0 + wm * 64 + 4 * (lane >> 5) + (i & 3) + 8 * (i >> 2);
;         const float* ra = resid_in ? xrow(p, row) : (xfq + (size_t)row * 1024);
;         const float* rb = resid_in ? xrow(p, row + 32) : (xfq + (size_t)(row + 32) * 1024);
;         acc00[i] = ra[cc0]; acc01[i] = ra[cc0 + 32];
;         acc10[i] = rb[cc0]; acc11[i] = rb[cc0 + 32];
;       }
;     } else {
; #pragma unroll
;       for (int i = 0; i < 16; i++) { acc00[i] = 0.f; acc01[i] = 0.f; acc10[i] = 0.f; acc11[i] = 0.f; }
;     }
;     float4 pq0 = make_float4(0.f, 0.f, 0.f, 0.f), pq1 = pq0, pq2 = pq0, pq3 = pq0;
;     if (EPI == EPI_SCALE || EPI == EPI_FF1) {
;       const float4* pp = (const float4*)(part + (size_t)(m0 + (tid & 255)) * 16);
;       pq0 = pp[0]; pq1 = pp[1]; pq2 = pp[2]; pq3 = pp[3];
;     }
;     __syncthreads();
;     WRITEX(0);
;     if (KT > 2) LOADX(2);
;     RAW_BARRIER();
;     for (int kt = 0; kt < KT; kt += 2) {
;       if (kt + 1 < KT) WRITEY(1);
;       if (kt + 3 < KT) LOADY(kt + 3);
;       COMPUTE(0);
;       RAW_BARRIER();
;       if (kt + 1 >= KT) break;
;       if (kt + 2 < KT) WRITEX(0);
;       if (kt + 4 < KT) LOADX(kt + 4);
;       COMPUTE(1);
;       RAW_BARRIER();
;     }
	v_mov_b32_e32 v239, 0
	global_store_dwordx2 v247, v[238:239], s[14:15] offset:2048
	s_nop 1
	v_mov_b32_e32 v238, v237
	v_mov_b32_e32 v239, 0
	global_store_dwordx2 v247, v[238:239], s[14:15] offset:3072
	s_nop 1
	v_mov_b64_e32 v[0:1], 0
	v_mov_b64_e32 v[2:3], 0
	v_mov_b64_e32 v[4:5], 0
	v_mov_b64_e32 v[6:7], 0
	v_mov_b64_e32 v[8:9], 0
	v_mov_b64_e32 v[10:11], 0
	v_mov_b64_e32 v[12:13], 0
	v_mov_b64_e32 v[14:15], 0
	v_mov_b64_e32 v[16:17], 0
	v_mov_b64_e32 v[18:19], 0
	v_mov_b64_e32 v[20:21], 0
	v_mov_b64_e32 v[22:23], 0
	v_mov_b64_e32 v[24:25], 0
	v_mov_b64_e32 v[26:27], 0
	v_mov_b64_e32 v[28:29], 0
	v_mov_b64_e32 v[30:31], 0
	v_mov_b64_e32 v[32:33], 0
	v_mov_b64_e32 v[34:35], 0
	v_mov_b64_e32 v[36:37], 0
	v_mov_b64_e32 v[38:39], 0
	v_mov_b64_e32 v[40:41], 0
	v_mov_b64_e32 v[42:43], 0
	v_mov_b64_e32 v[44:45], 0
	v_mov_b64_e32 v[46:47], 0
	v_mov_b64_e32 v[48:49], 0
	v_mov_b64_e32 v[50:51], 0
	v_mov_b64_e32 v[52:53], 0
	v_mov_b64_e32 v[54:55], 0
	v_mov_b64_e32 v[56:57], 0
	v_mov_b64_e32 v[58:59], 0
	v_mov_b64_e32 v[60:61], 0
	v_mov_b64_e32 v[62:63], 0
	v_mov_b64_e32 v[64:65], 0
	v_mov_b64_e32 v[66:67], 0
	v_mov_b64_e32 v[68:69], 0
	v_mov_b64_e32 v[70:71], 0
	v_mov_b64_e32 v[72:73], 0
	v_mov_b64_e32 v[74:75], 0
	v_mov_b64_e32 v[76:77], 0
	v_mov_b64_e32 v[78:79], 0
	v_mov_b64_e32 v[80:81], 0
	v_mov_b64_e32 v[82:83], 0
	v_mov_b64_e32 v[84:85], 0
	v_mov_b64_e32 v[86:87], 0
	v_mov_b64_e32 v[88:89], 0
	v_mov_b64_e32 v[90:91], 0
	v_mov_b64_e32 v[92:93], 0
	v_mov_b64_e32 v[94:95], 0
	v_mov_b64_e32 v[96:97], 0
	v_mov_b64_e32 v[98:99], 0
	v_mov_b64_e32 v[100:101], 0
	v_mov_b64_e32 v[102:103], 0
	v_mov_b64_e32 v[104:105], 0
	v_mov_b64_e32 v[106:107], 0
	v_mov_b64_e32 v[108:109], 0
	v_mov_b64_e32 v[110:111], 0
	v_mov_b64_e32 v[112:113], 0
	v_mov_b64_e32 v[114:115], 0
	v_mov_b64_e32 v[116:117], 0
	v_mov_b64_e32 v[118:119], 0
	v_mov_b64_e32 v[120:121], 0
	v_mov_b64_e32 v[122:123], 0
	v_mov_b64_e32 v[124:125], 0
	v_mov_b64_e32 v[126:127], 0
	v_mov_b64_e32 v[178:179], 0
	v_mov_b64_e32 v[180:181], 0
	v_mov_b64_e32 v[182:183], 0
	v_mov_b64_e32 v[184:185], 0
	v_mov_b64_e32 v[186:187], 0
	v_mov_b64_e32 v[188:189], 0
	v_mov_b64_e32 v[190:191], 0
	v_mov_b64_e32 v[192:193], 0
	v_mov_b64_e32 v[194:195], 0
	v_mov_b64_e32 v[196:197], 0
	v_mov_b64_e32 v[198:199], 0
	v_mov_b64_e32 v[200:201], 0
	v_mov_b64_e32 v[202:203], 0
	v_mov_b64_e32 v[204:205], 0
	v_mov_b64_e32 v[206:207], 0
	v_mov_b64_e32 v[208:209], 0
	v_mov_b64_e32 v[210:211], 0
	v_mov_b64_e32 v[212:213], 0
	v_mov_b64_e32 v[214:215], 0
	v_mov_b64_e32 v[216:217], 0
	v_mov_b64_e32 v[218:219], 0
	v_mov_b64_e32 v[220:221], 0
	v_mov_b64_e32 v[222:223], 0
	v_mov_b64_e32 v[224:225], 0
	s_branch .Lgc_next
.Lgc_loopN:
	ds_read_b128 v[130:133], v226
	ds_read_b128 v[146:149], v228
	ds_read_b128 v[150:153], v228 offset:2048
	ds_read_b128 v[154:157], v228 offset:4096
	ds_read_b128 v[158:161], v228 offset:6144
	ds_read_b128 v[162:165], v228 offset:8192
	ds_read_b128 v[166:169], v228 offset:10240
	ds_read_b128 v[170:173], v228 offset:12288
	ds_read_b128 v[174:177], v228 offset:14336
	ds_read_b128 v[134:137], v226 offset:2048
	ds_read_b128 v[138:141], v226 offset:4096
	ds_read_b128 v[142:145], v226 offset:6144
	v_mfma_f32_16x16x32_bf16 v[0:3], v[178:181], v[194:197], v[0:3]
	v_mfma_f32_16x16x32_bf16 v[4:7], v[178:181], v[198:201], v[4:7]
	v_mfma_f32_16x16x32_bf16 v[8:11], v[178:181], v[202:205], v[8:11]
	v_mfma_f32_16x16x32_bf16 v[12:15], v[178:181], v[206:209], v[12:15]
	v_mfma_f32_16x16x32_bf16 v[16:19], v[178:181], v[210:213], v[16:19]
	v_mfma_f32_16x16x32_bf16 v[20:23], v[178:181], v[214:217], v[20:23]
	v_mfma_f32_16x16x32_bf16 v[24:27], v[178:181], v[218:221], v[24:27]
	v_mfma_f32_16x16x32_bf16 v[28:31], v[178:181], v[222:225], v[28:31]
	v_mfma_f32_16x16x32_bf16 v[32:35], v[182:185], v[194:197], v[32:35]
	v_mfma_f32_16x16x32_bf16 v[36:39], v[182:185], v[198:201], v[36:39]
	v_mfma_f32_16x16x32_bf16 v[40:43], v[182:185], v[202:205], v[40:43]
	v_mfma_f32_16x16x32_bf16 v[44:47], v[182:185], v[206:209], v[44:47]
	v_mfma_f32_16x16x32_bf16 v[48:51], v[182:185], v[210:213], v[48:51]
	v_mfma_f32_16x16x32_bf16 v[52:55], v[182:185], v[214:217], v[52:55]
	v_mfma_f32_16x16x32_bf16 v[56:59], v[182:185], v[218:221], v[56:59]
	v_mfma_f32_16x16x32_bf16 v[60:63], v[182:185], v[222:225], v[60:63]
	v_mfma_f32_16x16x32_bf16 v[64:67], v[186:189], v[194:197], v[64:67]
	v_mfma_f32_16x16x32_bf16 v[68:71], v[186:189], v[198:201], v[68:71]
	v_mfma_f32_16x16x32_bf16 v[72:75], v[186:189], v[202:205], v[72:75]
	v_mfma_f32_16x16x32_bf16 v[76:79], v[186:189], v[206:209], v[76:79]
	v_mfma_f32_16x16x32_bf16 v[80:83], v[186:189], v[210:213], v[80:83]
	v_mfma_f32_16x16x32_bf16 v[84:87], v[186:189], v[214:217], v[84:87]
	v_mfma_f32_16x16x32_bf16 v[88:91], v[186:189], v[218:221], v[88:91]
	v_mfma_f32_16x16x32_bf16 v[92:95], v[186:189], v[222:225], v[92:95]
	v_mfma_f32_16x16x32_bf16 v[96:99], v[190:193], v[194:197], v[96:99]
	v_mfma_f32_16x16x32_bf16 v[100:103], v[190:193], v[198:201], v[100:103]
	v_mfma_f32_16x16x32_bf16 v[104:107], v[190:193], v[202:205], v[104:107]
	v_mfma_f32_16x16x32_bf16 v[108:111], v[190:193], v[206:209], v[108:111]
	v_mfma_f32_16x16x32_bf16 v[112:115], v[190:193], v[210:213], v[112:115]
	v_mfma_f32_16x16x32_bf16 v[116:119], v[190:193], v[214:217], v[116:119]
	v_mfma_f32_16x16x32_bf16 v[120:123], v[190:193], v[218:221], v[120:123]
	v_mfma_f32_16x16x32_bf16 v[124:127], v[190:193], v[222:225], v[124:127]
	ds_read_b128 v[178:181], v227
	ds_read_b128 v[194:197], v229
	ds_read_b128 v[198:201], v229 offset:2048
	ds_read_b128 v[202:205], v229 offset:4096
	ds_read_b128 v[206:209], v229 offset:6144
	ds_read_b128 v[210:213], v229 offset:8192
	ds_read_b128 v[214:217], v229 offset:10240
	ds_read_b128 v[218:221], v229 offset:12288
	ds_read_b128 v[222:225], v229 offset:14336
	ds_read_b128 v[182:185], v227 offset:2048
	ds_read_b128 v[186:189], v227 offset:4096
	ds_read_b128 v[190:193], v227 offset:6144
	s_waitcnt lgkmcnt(12)
; #define RAW_BARRIER() do { asm volatile("s_waitcnt lgkmcnt(0)" ::: "memory"); __builtin_amdgcn_s_barrier(); asm volatile("" ::: "memory"); } while (0)
; template <int EPI>
; __device__ __forceinline__ void gemm_phase(const Params& p, const u16* __restrict__ A, int lda, const u16* __restrict__ BT, int ldb,
;                            int K, int N, u16* __restrict__ outb, int ldo, int resid_in, int boff) {
;     ...
;     LOADX(0);
;     if (KT > 1) LOADY(1);
;     f32x16 acc00, acc01, acc10, acc11;
;     if (EPI == EPI_RES && !part_unit) {
;       const int cc0 = n0 + wn * 64 + (lane & 31);
;       float* xfq = p.out;
; #pragma unroll
;       for (int i = 0; i < 16; i++) {
;         const int row = m0 + wm * 64 + 4 * (lane >> 5) + (i & 3) + 8 * (i >> 2);
;         const float* ra = resid_in ? xrow(p, row) : (xfq + (size_t)row * 1024);
;         const float* rb = resid_in ? xrow(p, row + 32) : (xfq + (size_t)(row + 32) * 1024);
;         acc00[i] = ra[cc0]; acc01[i] = ra[cc0 + 32];
;         acc10[i] = rb[cc0]; acc11[i] = rb[cc0 + 32];
;       }
;     } else {
; #pragma unroll
;       for (int i = 0; i < 16; i++) { acc00[i] = 0.f; acc01[i] = 0.f; acc10[i] = 0.f; acc11[i] = 0.f; }
;     }
;     float4 pq0 = make_float4(0.f, 0.f, 0.f, 0.f), pq1 = pq0, pq2 = pq0, pq3 = pq0;
;     if (EPI == EPI_SCALE || EPI == EPI_FF1) {
;       const float4* pp = (const float4*)(part + (size_t)(m0 + (tid & 255)) * 16);
;       pq0 = pp[0]; pq1 = pp[1]; pq2 = pp[2]; pq3 = pp[3];
;     }
;     __syncthreads();
;     WRITEX(0);
;     if (KT > 2) LOADX(2);
;     RAW_BARRIER();
;     for (int kt = 0; kt < KT; kt += 2) {
;       if (kt + 1 < KT) WRITEY(1);
;       if (kt + 3 < KT) LOADY(kt + 3);
;       COMPUTE(0);
;       RAW_BARRIER();
;       if (kt + 1 >= KT) break;
;       if (kt + 2 < KT) WRITEX(0);
;       if (kt + 4 < KT) LOADX(kt + 4);
;       COMPUTE(1);
;       RAW_BARRIER();
;     }
;     ...
;     if (EPI == EPI_RES && part_unit) {
;       float* xfp = p.out;
; #pragma unroll
;       for (int i = 0; i < 16; i++) {
;         const int rl = wm * 64 + 4 * (lane >> 5) + (i & 3) + 8 * (i >> 2);
;         float* r0p = xfp + (size_t)(m0 + rl) * 1024;
;         float* r1p = r0p + (size_t)32 * 1024;
;         atomicAdd(r0p + c0, acc00[i]); atomicAdd(r0p + c1, acc01[i]);
;         atomicAdd(r1p + c0, acc10[i]); atomicAdd(r1p + c1, acc11[i]);
;       }
	v_mfma_f32_16x16x32_bf16 v[0:3], v[130:133], v[146:149], v[0:3]
	v_mfma_f32_16x16x32_bf16 v[4:7], v[130:133], v[150:153], v[4:7]
	v_mfma_f32_16x16x32_bf16 v[8:11], v[130:133], v[154:157], v[8:11]
	v_mfma_f32_16x16x32_bf16 v[12:15], v[130:133], v[158:161], v[12:15]
	v_mfma_f32_16x16x32_bf16 v[16:19], v[130:133], v[162:165], v[16:19]
	v_mfma_f32_16x16x32_bf16 v[20:23], v[130:133], v[166:169], v[20:23]
	v_mfma_f32_16x16x32_bf16 v[24:27], v[130:133], v[170:173], v[24:27]
	v_mfma_f32_16x16x32_bf16 v[28:31], v[130:133], v[174:177], v[28:31]
	v_mfma_f32_16x16x32_bf16 v[32:35], v[134:137], v[146:149], v[32:35]
	v_add_u32_e32 v226, s31, v226
	v_mfma_f32_16x16x32_bf16 v[36:39], v[134:137], v[150:153], v[36:39]
	v_add_u32_e32 v227, s31, v227
	v_mfma_f32_16x16x32_bf16 v[40:43], v[134:137], v[154:157], v[40:43]
	v_add_u32_e32 v228, s31, v228
	v_mfma_f32_16x16x32_bf16 v[44:47], v[134:137], v[158:161], v[44:47]
	v_add_u32_e32 v229, s31, v229
	v_mfma_f32_16x16x32_bf16 v[48:51], v[134:137], v[162:165], v[48:51]
	v_mfma_f32_16x16x32_bf16 v[52:55], v[134:137], v[166:169], v[52:55]
	v_mfma_f32_16x16x32_bf16 v[56:59], v[134:137], v[170:173], v[56:59]
	v_mfma_f32_16x16x32_bf16 v[60:63], v[134:137], v[174:177], v[60:63]
	v_mfma_f32_16x16x32_bf16 v[64:67], v[138:141], v[146:149], v[64:67]
	v_mfma_f32_16x16x32_bf16 v[68:71], v[138:141], v[150:153], v[68:71]
	v_mfma_f32_16x16x32_bf16 v[72:75], v[138:141], v[154:157], v[72:75]
	v_mfma_f32_16x16x32_bf16 v[76:79], v[138:141], v[158:161], v[76:79]
	v_mfma_f32_16x16x32_bf16 v[80:83], v[138:141], v[162:165], v[80:83]
	v_mfma_f32_16x16x32_bf16 v[84:87], v[138:141], v[166:169], v[84:87]
	v_mfma_f32_16x16x32_bf16 v[88:91], v[138:141], v[170:173], v[88:91]
	v_mfma_f32_16x16x32_bf16 v[92:95], v[138:141], v[174:177], v[92:95]
	v_mfma_f32_16x16x32_bf16 v[96:99], v[142:145], v[146:149], v[96:99]
	v_mfma_f32_16x16x32_bf16 v[100:103], v[142:145], v[150:153], v[100:103]
	v_mfma_f32_16x16x32_bf16 v[104:107], v[142:145], v[154:157], v[104:107]
	v_mfma_f32_16x16x32_bf16 v[108:111], v[142:145], v[158:161], v[108:111]
	v_mfma_f32_16x16x32_bf16 v[112:115], v[142:145], v[162:165], v[112:115]
	v_mfma_f32_16x16x32_bf16 v[116:119], v[142:145], v[166:169], v[116:119]
	v_mfma_f32_16x16x32_bf16 v[120:123], v[142:145], v[170:173], v[120:123]
	v_mfma_f32_16x16x32_bf16 v[124:127], v[142:145], v[174:177], v[124:127]
	s_add_u32 s13, s13, 1
	s_cmp_eq_u32 s13, 3
	s_cselect_b32 s13, 0, s13
	s_cmp_eq_u32 s13, 2
	s_cselect_b32 s31, s34, s35
	s_waitcnt lgkmcnt(0)
	s_barrier
	s_sub_u32 s18, s18, 1
	s_cmp_lg_u32 s18, 0
	s_cbranch_scc1 .Lgc_loopN
	v_mfma_f32_16x16x32_bf16 v[0:3], v[178:181], v[194:197], v[0:3]
	v_mfma_f32_16x16x32_bf16 v[4:7], v[178:181], v[198:201], v[4:7]
	v_mfma_f32_16x16x32_bf16 v[8:11], v[178:181], v[202:205], v[8:11]
	v_mfma_f32_16x16x32_bf16 v[12:15], v[178:181], v[206:209], v[12:15]
	v_mfma_f32_16x16x32_bf16 v[16:19], v[178:181], v[210:213], v[16:19]
	v_mfma_f32_16x16x32_bf16 v[20:23], v[178:181], v[214:217], v[20:23]
	v_mfma_f32_16x16x32_bf16 v[24:27], v[178:181], v[218:221], v[24:27]
	v_mfma_f32_16x16x32_bf16 v[28:31], v[178:181], v[222:225], v[28:31]
	v_mfma_f32_16x16x32_bf16 v[32:35], v[182:185], v[194:197], v[32:35]
	v_mfma_f32_16x16x32_bf16 v[36:39], v[182:185], v[198:201], v[36:39]
	v_mfma_f32_16x16x32_bf16 v[40:43], v[182:185], v[202:205], v[40:43]
	v_mfma_f32_16x16x32_bf16 v[44:47], v[182:185], v[206:209], v[44:47]
	v_mfma_f32_16x16x32_bf16 v[48:51], v[182:185], v[210:213], v[48:51]
	v_mfma_f32_16x16x32_bf16 v[52:55], v[182:185], v[214:217], v[52:55]
	v_mfma_f32_16x16x32_bf16 v[56:59], v[182:185], v[218:221], v[56:59]
	v_mfma_f32_16x16x32_bf16 v[60:63], v[182:185], v[222:225], v[60:63]
	v_mfma_f32_16x16x32_bf16 v[64:67], v[186:189], v[194:197], v[64:67]
	v_mfma_f32_16x16x32_bf16 v[68:71], v[186:189], v[198:201], v[68:71]
	v_mfma_f32_16x16x32_bf16 v[72:75], v[186:189], v[202:205], v[72:75]
	v_mfma_f32_16x16x32_bf16 v[76:79], v[186:189], v[206:209], v[76:79]
	v_mfma_f32_16x16x32_bf16 v[80:83], v[186:189], v[210:213], v[80:83]
	v_mfma_f32_16x16x32_bf16 v[84:87], v[186:189], v[214:217], v[84:87]
	v_mfma_f32_16x16x32_bf16 v[88:91], v[186:189], v[218:221], v[88:91]
	v_mfma_f32_16x16x32_bf16 v[92:95], v[186:189], v[222:225], v[92:95]
	v_mfma_f32_16x16x32_bf16 v[96:99], v[190:193], v[194:197], v[96:99]
	v_mfma_f32_16x16x32_bf16 v[100:103], v[190:193], v[198:201], v[100:103]
	v_mfma_f32_16x16x32_bf16 v[104:107], v[190:193], v[202:205], v[104:107]
	v_mfma_f32_16x16x32_bf16 v[108:111], v[190:193], v[206:209], v[108:111]
	v_mfma_f32_16x16x32_bf16 v[112:115], v[190:193], v[210:213], v[112:115]
	v_mfma_f32_16x16x32_bf16 v[116:119], v[190:193], v[214:217], v[116:119]
	v_mfma_f32_16x16x32_bf16 v[120:123], v[190:193], v[218:221], v[120:123]
	v_mfma_f32_16x16x32_bf16 v[124:127], v[190:193], v[222:225], v[124:127]
	s_lshl_b32 s11, s6, 8
	s_lshl_b32 s12, s4, 6
	s_add_u32 s11, s11, s12
	v_add_u32_e32 v238, s11, v248
	v_sub_u32_e32 v238, v238, v248
	v_lshl_add_u32 v238, v249, 2, v238
	v_lshlrev_b32_e32 v243, 12, v238
	s_lshl_b32 s11, s7, 7
	v_add_u32_e32 v239, s11, v248
	v_lshlrev_b32_e32 v239, 2, v239
	v_add_u32_e32 v243, v243, v239
	s_nop 7
	s_mov_b32 s36, s94
	s_mov_b32 s37, s95
	global_atomic_add_f32 v243, v0, s[36:37]
	global_atomic_add_f32 v243, v4, s[36:37] offset:64
	global_atomic_add_f32 v243, v8, s[36:37] offset:128
	global_atomic_add_f32 v243, v12, s[36:37] offset:192
	global_atomic_add_f32 v243, v16, s[36:37] offset:256
	global_atomic_add_f32 v243, v20, s[36:37] offset:320
	global_atomic_add_f32 v243, v24, s[36:37] offset:384
	global_atomic_add_f32 v243, v28, s[36:37] offset:448
	s_add_u32 s36, s36, 0x1000
	s_addc_u32 s37, s37, 0
; template <int EPI>
; __device__ __forceinline__ void gemm_phase(const Params& p, const u16* __restrict__ A, int lda, const u16* __restrict__ BT, int ldb,
;                            int K, int N, u16* __restrict__ outb, int ldo, int resid_in, int boff) {
;     ...
;     if (EPI == EPI_RES && part_unit) {
;       float* xfp = p.out;
; #pragma unroll
;       for (int i = 0; i < 16; i++) {
;         const int rl = wm * 64 + 4 * (lane >> 5) + (i & 3) + 8 * (i >> 2);
;         float* r0p = xfp + (size_t)(m0 + rl) * 1024;
;         float* r1p = r0p + (size_t)32 * 1024;
;         atomicAdd(r0p + c0, acc00[i]); atomicAdd(r0p + c1, acc01[i]);
;         atomicAdd(r1p + c0, acc10[i]); atomicAdd(r1p + c1, acc11[i]);
;       }
	global_atomic_add_f32 v243, v1, s[36:37]
	global_atomic_add_f32 v243, v5, s[36:37] offset:64
	global_atomic_add_f32 v243, v9, s[36:37] offset:128
	global_atomic_add_f32 v243, v13, s[36:37] offset:192
	global_atomic_add_f32 v243, v17, s[36:37] offset:256
	global_atomic_add_f32 v243, v21, s[36:37] offset:320
	global_atomic_add_f32 v243, v25, s[36:37] offset:384
	global_atomic_add_f32 v243, v29, s[36:37] offset:448
	s_add_u32 s36, s36, 0x1000
	s_addc_u32 s37, s37, 0
	global_atomic_add_f32 v243, v2, s[36:37]
	global_atomic_add_f32 v243, v6, s[36:37] offset:64
	global_atomic_add_f32 v243, v10, s[36:37] offset:128
	global_atomic_add_f32 v243, v14, s[36:37] offset:192
	global_atomic_add_f32 v243, v18, s[36:37] offset:256
	global_atomic_add_f32 v243, v22, s[36:37] offset:320
	global_atomic_add_f32 v243, v26, s[36:37] offset:384
	global_atomic_add_f32 v243, v30, s[36:37] offset:448
	s_add_u32 s36, s36, 0x1000
	s_addc_u32 s37, s37, 0
	global_atomic_add_f32 v243, v3, s[36:37]
	global_atomic_add_f32 v243, v7, s[36:37] offset:64
	global_atomic_add_f32 v243, v11, s[36:37] offset:128
	global_atomic_add_f32 v243, v15, s[36:37] offset:192
	global_atomic_add_f32 v243, v19, s[36:37] offset:256
	global_atomic_add_f32 v243, v23, s[36:37] offset:320
	global_atomic_add_f32 v243, v27, s[36:37] offset:384
	global_atomic_add_f32 v243, v31, s[36:37] offset:448
	s_add_u32 s36, s36, 0xd000
	s_addc_u32 s37, s37, 0
	global_atomic_add_f32 v243, v32, s[36:37]
	global_atomic_add_f32 v243, v36, s[36:37] offset:64
	global_atomic_add_f32 v243, v40, s[36:37] offset:128
	global_atomic_add_f32 v243, v44, s[36:37] offset:192
	global_atomic_add_f32 v243, v48, s[36:37] offset:256
	global_atomic_add_f32 v243, v52, s[36:37] offset:320
	global_atomic_add_f32 v243, v56, s[36:37] offset:384
	global_atomic_add_f32 v243, v60, s[36:37] offset:448
	s_add_u32 s36, s36, 0x1000
	s_addc_u32 s37, s37, 0
	global_atomic_add_f32 v243, v33, s[36:37]
	global_atomic_add_f32 v243, v37, s[36:37] offset:64
	global_atomic_add_f32 v243, v41, s[36:37] offset:128
	global_atomic_add_f32 v243, v45, s[36:37] offset:192
	global_atomic_add_f32 v243, v49, s[36:37] offset:256
	global_atomic_add_f32 v243, v53, s[36:37] offset:320
	global_atomic_add_f32 v243, v57, s[36:37] offset:384
	global_atomic_add_f32 v243, v61, s[36:37] offset:448
	s_add_u32 s36, s36, 0x1000
	s_addc_u32 s37, s37, 0
	global_atomic_add_f32 v243, v34, s[36:37]
	global_atomic_add_f32 v243, v38, s[36:37] offset:64
	global_atomic_add_f32 v243, v42, s[36:37] offset:128
	global_atomic_add_f32 v243, v46, s[36:37] offset:192
	global_atomic_add_f32 v243, v50, s[36:37] offset:256
	global_atomic_add_f32 v243, v54, s[36:37] offset:320
	global_atomic_add_f32 v243, v58, s[36:37] offset:384
	global_atomic_add_f32 v243, v62, s[36:37] offset:448
	s_add_u32 s36, s36, 0x1000
	s_addc_u32 s37, s37, 0
	global_atomic_add_f32 v243, v35, s[36:37]
	global_atomic_add_f32 v243, v39, s[36:37] offset:64
	global_atomic_add_f32 v243, v43, s[36:37] offset:128
	global_atomic_add_f32 v243, v47, s[36:37] offset:192
	global_atomic_add_f32 v243, v51, s[36:37] offset:256
	global_atomic_add_f32 v243, v55, s[36:37] offset:320
	global_atomic_add_f32 v243, v59, s[36:37] offset:384
	global_atomic_add_f32 v243, v63, s[36:37] offset:448
	s_add_u32 s36, s36, 0xd000
	s_addc_u32 s37, s37, 0
	global_atomic_add_f32 v243, v64, s[36:37]
	global_atomic_add_f32 v243, v68, s[36:37] offset:64
	global_atomic_add_f32 v243, v72, s[36:37] offset:128
	global_atomic_add_f32 v243, v76, s[36:37] offset:192
	global_atomic_add_f32 v243, v80, s[36:37] offset:256
	global_atomic_add_f32 v243, v84, s[36:37] offset:320
	global_atomic_add_f32 v243, v88, s[36:37] offset:384
	global_atomic_add_f32 v243, v92, s[36:37] offset:448
	s_add_u32 s36, s36, 0x1000
	s_addc_u32 s37, s37, 0
	global_atomic_add_f32 v243, v65, s[36:37]
	global_atomic_add_f32 v243, v69, s[36:37] offset:64
	global_atomic_add_f32 v243, v73, s[36:37] offset:128
	global_atomic_add_f32 v243, v77, s[36:37] offset:192
	global_atomic_add_f32 v243, v81, s[36:37] offset:256
	global_atomic_add_f32 v243, v85, s[36:37] offset:320
	global_atomic_add_f32 v243, v89, s[36:37] offset:384
	global_atomic_add_f32 v243, v93, s[36:37] offset:448
	s_add_u32 s36, s36, 0x1000
	s_addc_u32 s37, s37, 0
	global_atomic_add_f32 v243, v66, s[36:37]
	global_atomic_add_f32 v243, v70, s[36:37] offset:64
	global_atomic_add_f32 v243, v74, s[36:37] offset:128
	global_atomic_add_f32 v243, v78, s[36:37] offset:192
	global_atomic_add_f32 v243, v82, s[36:37] offset:256
	global_atomic_add_f32 v243, v86, s[36:37] offset:320
	global_atomic_add_f32 v243, v90, s[36:37] offset:384
	global_atomic_add_f32 v243, v94, s[36:37] offset:448
	s_add_u32 s36, s36, 0x1000
	s_addc_u32 s37, s37, 0
	global_atomic_add_f32 v243, v67, s[36:37]
; template <int EPI>
; __device__ __forceinline__ void gemm_phase(const Params& p, const u16* __restrict__ A, int lda, const u16* __restrict__ BT, int ldb,
;                            int K, int N, u16* __restrict__ outb, int ldo, int resid_in, int boff) {
;     ...
;     if (EPI == EPI_RES && part_unit) {
;       float* xfp = p.out;
; #pragma unroll
;       for (int i = 0; i < 16; i++) {
;         const int rl = wm * 64 + 4 * (lane >> 5) + (i & 3) + 8 * (i >> 2);
;         float* r0p = xfp + (size_t)(m0 + rl) * 1024;
;         float* r1p = r0p + (size_t)32 * 1024;
;         atomicAdd(r0p + c0, acc00[i]); atomicAdd(r0p + c1, acc01[i]);
;         atomicAdd(r1p + c0, acc10[i]); atomicAdd(r1p + c1, acc11[i]);
;       }
	global_atomic_add_f32 v243, v71, s[36:37] offset:64
	global_atomic_add_f32 v243, v75, s[36:37] offset:128
	global_atomic_add_f32 v243, v79, s[36:37] offset:192
	global_atomic_add_f32 v243, v83, s[36:37] offset:256
	global_atomic_add_f32 v243, v87, s[36:37] offset:320
	global_atomic_add_f32 v243, v91, s[36:37] offset:384
	global_atomic_add_f32 v243, v95, s[36:37] offset:448
	s_add_u32 s36, s36, 0xd000
	s_addc_u32 s37, s37, 0
	global_atomic_add_f32 v243, v96, s[36:37]
	global_atomic_add_f32 v243, v100, s[36:37] offset:64
	global_atomic_add_f32 v243, v104, s[36:37] offset:128
	global_atomic_add_f32 v243, v108, s[36:37] offset:192
	global_atomic_add_f32 v243, v112, s[36:37] offset:256
	global_atomic_add_f32 v243, v116, s[36:37] offset:320
	global_atomic_add_f32 v243, v120, s[36:37] offset:384
	global_atomic_add_f32 v243, v124, s[36:37] offset:448
	s_add_u32 s36, s36, 0x1000
	s_addc_u32 s37, s37, 0
	global_atomic_add_f32 v243, v97, s[36:37]
	global_atomic_add_f32 v243, v101, s[36:37] offset:64
	global_atomic_add_f32 v243, v105, s[36:37] offset:128
	global_atomic_add_f32 v243, v109, s[36:37] offset:192
	global_atomic_add_f32 v243, v113, s[36:37] offset:256
	global_atomic_add_f32 v243, v117, s[36:37] offset:320
	global_atomic_add_f32 v243, v121, s[36:37] offset:384
	global_atomic_add_f32 v243, v125, s[36:37] offset:448
	s_add_u32 s36, s36, 0x1000
	s_addc_u32 s37, s37, 0
	global_atomic_add_f32 v243, v98, s[36:37]
	global_atomic_add_f32 v243, v102, s[36:37] offset:64
	global_atomic_add_f32 v243, v106, s[36:37] offset:128
	global_atomic_add_f32 v243, v110, s[36:37] offset:192
	global_atomic_add_f32 v243, v114, s[36:37] offset:256
	global_atomic_add_f32 v243, v118, s[36:37] offset:320
	global_atomic_add_f32 v243, v122, s[36:37] offset:384
	global_atomic_add_f32 v243, v126, s[36:37] offset:448
	s_add_u32 s36, s36, 0x1000
	s_addc_u32 s37, s37, 0
	global_atomic_add_f32 v243, v99, s[36:37]
	global_atomic_add_f32 v243, v103, s[36:37] offset:64
	global_atomic_add_f32 v243, v107, s[36:37] offset:128
	global_atomic_add_f32 v243, v111, s[36:37] offset:192
	global_atomic_add_f32 v243, v115, s[36:37] offset:256
	global_atomic_add_f32 v243, v119, s[36:37] offset:320
	global_atomic_add_f32 v243, v123, s[36:37] offset:384
	global_atomic_add_f32 v243, v127, s[36:37] offset:448
	s_nop 3
	v_mov_b64_e32 v[0:1], 0
	v_mov_b64_e32 v[2:3], 0
	v_mov_b64_e32 v[4:5], 0
	v_mov_b64_e32 v[6:7], 0
	v_mov_b64_e32 v[8:9], 0
	v_mov_b64_e32 v[10:11], 0
	v_mov_b64_e32 v[12:13], 0
	v_mov_b64_e32 v[14:15], 0
	v_mov_b64_e32 v[16:17], 0
	v_mov_b64_e32 v[18:19], 0
	v_mov_b64_e32 v[20:21], 0
	v_mov_b64_e32 v[22:23], 0
	v_mov_b64_e32 v[24:25], 0
	v_mov_b64_e32 v[26:27], 0
	v_mov_b64_e32 v[28:29], 0
	v_mov_b64_e32 v[30:31], 0
	v_mov_b64_e32 v[32:33], 0
	v_mov_b64_e32 v[34:35], 0
	v_mov_b64_e32 v[36:37], 0
	v_mov_b64_e32 v[38:39], 0
	v_mov_b64_e32 v[40:41], 0
	v_mov_b64_e32 v[42:43], 0
	v_mov_b64_e32 v[44:45], 0
	v_mov_b64_e32 v[46:47], 0
	v_mov_b64_e32 v[48:49], 0
	v_mov_b64_e32 v[50:51], 0
	v_mov_b64_e32 v[52:53], 0
	v_mov_b64_e32 v[54:55], 0
	v_mov_b64_e32 v[56:57], 0
	v_mov_b64_e32 v[58:59], 0
	v_mov_b64_e32 v[60:61], 0
	v_mov_b64_e32 v[62:63], 0
	v_mov_b64_e32 v[64:65], 0
	v_mov_b64_e32 v[66:67], 0
	v_mov_b64_e32 v[68:69], 0
	v_mov_b64_e32 v[70:71], 0
	v_mov_b64_e32 v[72:73], 0
	v_mov_b64_e32 v[74:75], 0
	v_mov_b64_e32 v[76:77], 0
	v_mov_b64_e32 v[78:79], 0
	v_mov_b64_e32 v[80:81], 0
	v_mov_b64_e32 v[82:83], 0
	v_mov_b64_e32 v[84:85], 0
	v_mov_b64_e32 v[86:87], 0
	v_mov_b64_e32 v[88:89], 0
	v_mov_b64_e32 v[90:91], 0
	v_mov_b64_e32 v[92:93], 0
	v_mov_b64_e32 v[94:95], 0
	v_mov_b64_e32 v[96:97], 0
	v_mov_b64_e32 v[98:99], 0
	v_mov_b64_e32 v[100:101], 0
	v_mov_b64_e32 v[102:103], 0
	v_mov_b64_e32 v[104:105], 0
	v_mov_b64_e32 v[106:107], 0
	v_mov_b64_e32 v[108:109], 0
	v_mov_b64_e32 v[110:111], 0
	v_mov_b64_e32 v[112:113], 0
	v_mov_b64_e32 v[114:115], 0
	v_mov_b64_e32 v[116:117], 0
	v_mov_b64_e32 v[118:119], 0
	v_mov_b64_e32 v[120:121], 0
	v_mov_b64_e32 v[122:123], 0
	v_mov_b64_e32 v[124:125], 0
	v_mov_b64_e32 v[126:127], 0
	v_mov_b64_e32 v[178:179], 0
	v_mov_b64_e32 v[180:181], 0
	v_mov_b64_e32 v[182:183], 0
	v_mov_b64_e32 v[184:185], 0
	v_mov_b64_e32 v[186:187], 0
	v_mov_b64_e32 v[188:189], 0
	v_mov_b64_e32 v[190:191], 0
	v_mov_b64_e32 v[192:193], 0
	v_mov_b64_e32 v[194:195], 0
	v_mov_b64_e32 v[196:197], 0
	v_mov_b64_e32 v[198:199], 0
	v_mov_b64_e32 v[200:201], 0
	v_mov_b64_e32 v[202:203], 0
	v_mov_b64_e32 v[204:205], 0
	v_mov_b64_e32 v[206:207], 0
	v_mov_b64_e32 v[208:209], 0
	v_mov_b64_e32 v[210:211], 0
	v_mov_b64_e32 v[212:213], 0
	v_mov_b64_e32 v[214:215], 0
	v_mov_b64_e32 v[216:217], 0
	v_mov_b64_e32 v[218:219], 0
	v_mov_b64_e32 v[220:221], 0
	v_mov_b64_e32 v[222:223], 0
	v_mov_b64_e32 v[224:225], 0
